# v40 stack + burst edges trimmed: setprio raised before the pre-burst barrier, redundant lgkmcnt(0) dropped, setprio lowered after the post-burst barrier
# speedup vs baseline: 1.0054x; 1.0020x over previous
; #define PG8_LDA(dst, b, h) do { if constexpr (FP8) { _Pragma("unroll") for (int m = 0; m < 4; ++m) dst##8[m] = PG8_LD8(PG8_SA(b, h), aoff, aoff1, m); } \
;         else { _Pragma("unroll") for (int m = 0; m < 4; ++m) _Pragma("unroll") for (int k = 0; k < 2; ++k) dst[m][k] = *(const LAS bf16x8*)(lds + PG8_SA(b, h) + (k ? aoff1 : aoff) + m * 2048); } } while (0)
; #define PG8_LDB(dst, b, h) do { if constexpr (FP8) { dst##8[0] = PG8_LD8(PG8_SB(b, h), boff, boff1, 0); dst##8[1] = PG8_LD8(PG8_SB(b, h), boff, boff1, 1); } \
;         else { _Pragma("unroll") for (int n = 0; n < 2; ++n) _Pragma("unroll") for (int k = 0; k < 2; ++k) dst[n][k] = *(const LAS bf16x8*)(lds + PG8_SB(b, h) + (k ? boff1 : boff) + n * 2048); } } while (0)
; #define PG8_WAIT_V(n) asm volatile("s_waitcnt vmcnt(" #n ")" ::: "memory")
; #define PG8_WAIT_L(n) asm volatile("s_waitcnt lgkmcnt(" #n ")" ::: "memory")
; #define PG8_BAR __builtin_amdgcn_s_barrier()
; #define PG8_SCHED __builtin_amdgcn_sched_barrier(0)
; #define PG8_S1 PG8_STAGE(PG8_SA(1, 1), a1 + hstepA, voffA)
; #define PG8_S2 do { PG8_STAGE(PG8_SB(0, 0), b2, voffB); PG8_STAGE(PG8_SB(0, 1), b2 + hstepB, voffB); PG8_STAGE(PG8_SA(0, 0), a2, voffA); } while (0)
; template <class Epi, class SchedT, bool ALIGN_EPI, bool SP2, bool FP8 = false>
; __device__ __forceinline__ void gemm_phase(LAS unsigned char* lds, const Gemm g, const SchedT& S, const Epi& E, const int wid) {
;     ...
;         for (int t = 0; t < nt; t += 2) {
;             const bool last = (t == nt - 2);
;             const char* a1 = cA + (size_t)(t + 1) * kstep;
;             const char* a2 = last ? nA : cA + (size_t)(t + 2) * kstep; const char* b2 = last ? nB : cB + (size_t)(t + 2) * kstep;
;             const char* a3 = a2 + kstep; const char* b3 = b2 + kstep;
;             if constexpr (SP2) {
;     ...
;             PG8_LDB(B0, 0, 0); PG8_LDB(B1, 0, 1); PG8_SCHED; PG8_LDA(At, 0, 0); PG8_S1;
;             PG8_WAIT_V(8); PG8_WAIT_L(0); PG8_BAR; PG8_MMAP(0, 0, 0); PG8_BAR; PG8_SCHED;
;             PG8_LDA(At, 0, 1); PG8_S2;
;             PG8_WAIT_V(8); PG8_WAIT_L(0); PG8_BAR; PG8_MMAP(1, 0, 1); PG8_BAR; PG8_SCHED;
.LBB0_239:
	ds_read_b128 v[130:133], v143
	ds_read_b128 v[134:137], v143 offset:16
	ds_read_b128 v[148:151], v143 offset:2048
	ds_read_b128 v[152:155], v143 offset:2064
	ds_read_b128 v[156:159], v144
	ds_read_b128 v[160:163], v144 offset:16
	ds_read_b128 v[164:167], v144 offset:2048
	ds_read_b128 v[168:171], v144 offset:2064
	s_add_i32 s30, s31, 2
	s_add_u32 s6, s52, 0xfff70080
	s_addc_u32 s7, s53, -1
	s_cmp_eq_u32 s20, s31
	s_cselect_b32 s67, s49, s7
	s_cselect_b32 s66, s48, s6
	v_mov_b32_e32 v128, v138
	ds_read_b128 v[172:175], v145
	ds_read_b128 v[176:179], v145 offset:16
	ds_read_b128 v[180:183], v145 offset:2048
	ds_read_b128 v[184:187], v145 offset:2064
	ds_read_b128 v[188:191], v145 offset:4096
	ds_read_b128 v[192:195], v145 offset:4112
	ds_read_b128 v[196:199], v145 offset:6144
	ds_read_b128 v[200:203], v145 offset:6160
	s_cselect_b32 s69, s8, s24
	s_cselect_b32 s68, s9, s21
	s_add_i32 m0, s87, 0xc000
	s_nop 0
	global_load_lds_dwordx4 v128, s[52:53]
	v_mov_b32_e32 v128, v140
	s_add_i32 m0, s87, 0xe000
	s_nop 0
	global_load_lds_dwordx4 v128, s[52:53]
	s_waitcnt vmcnt(8)
	s_waitcnt lgkmcnt(0)
	s_setprio 1
	s_barrier
	v_mfma_scale_f32_16x16x128_f8f6f4 v[124:127], v[130:137], v[172:179], v[124:127], v146, v146 op_sel_hi:[0,0,0]
	v_mfma_scale_f32_16x16x128_f8f6f4 v[108:111], v[156:163], v[172:179], v[108:111], v146, v146 op_sel_hi:[0,0,0]
	v_mfma_scale_f32_16x16x128_f8f6f4 v[120:123], v[148:155], v[172:179], v[120:123], v146, v146 op_sel_hi:[0,0,0]
	v_mfma_scale_f32_16x16x128_f8f6f4 v[100:103], v[164:171], v[172:179], v[100:103], v146, v146 op_sel_hi:[0,0,0]
	v_mfma_scale_f32_16x16x128_f8f6f4 v[116:119], v[130:137], v[180:187], v[116:119], v146, v146 op_sel_hi:[0,0,0]
	v_mfma_scale_f32_16x16x128_f8f6f4 v[112:115], v[148:155], v[180:187], v[112:115], v146, v146 op_sel_hi:[0,0,0]
	v_mfma_scale_f32_16x16x128_f8f6f4 v[104:107], v[130:137], v[188:195], v[104:107], v146, v146 op_sel_hi:[0,0,0]
	v_mfma_scale_f32_16x16x128_f8f6f4 v[60:63], v[164:171], v[196:203], v[60:63], v146, v146 op_sel_hi:[0,0,0]
	v_mfma_scale_f32_16x16x128_f8f6f4 v[172:175], v[156:163], v[180:187], v[92:95], v146, v146 op_sel_hi:[0,0,0]
	v_mfma_scale_f32_16x16x128_f8f6f4 v[176:179], v[164:171], v[180:187], v[84:87], v146, v146 op_sel_hi:[0,0,0]
	v_mfma_scale_f32_16x16x128_f8f6f4 v[180:183], v[156:163], v[188:195], v[76:79], v146, v146 op_sel_hi:[0,0,0]
	v_mfma_scale_f32_16x16x128_f8f6f4 v[184:187], v[148:155], v[188:195], v[96:99], v146, v146 op_sel_hi:[0,0,0]
	v_mfma_scale_f32_16x16x128_f8f6f4 v[188:191], v[164:171], v[188:195], v[72:75], v146, v146 op_sel_hi:[0,0,0]
	v_mfma_scale_f32_16x16x128_f8f6f4 v[192:195], v[130:137], v[196:203], v[88:91], v146, v146 op_sel_hi:[0,0,0]
	v_mfma_scale_f32_16x16x128_f8f6f4 v[204:207], v[156:163], v[196:203], v[68:71], v146, v146 op_sel_hi:[0,0,0]
	v_mfma_scale_f32_16x16x128_f8f6f4 v[208:211], v[148:155], v[196:203], v[80:83], v146, v146 op_sel_hi:[0,0,0]
	s_barrier
	s_setprio 0
	v_mov_b32_e32 v128, v139
	s_add_i32 s6, s94, s86
	s_nop 1
	ds_read_b128 v[68:71], v145 offset:16384
	ds_read_b128 v[72:75], v145 offset:16400
	ds_read_b128 v[76:79], v145 offset:18432
	ds_read_b128 v[80:83], v145 offset:18448
	ds_read_b128 v[84:87], v145 offset:20480
	ds_read_b128 v[88:91], v145 offset:20496
	ds_read_b128 v[92:95], v145 offset:22528
	ds_read_b128 v[96:99], v145 offset:22544
	s_mov_b32 m0, s6
	s_nop 0
	global_load_lds_dwordx4 v128, s[68:69]
	v_mov_b32_e32 v128, v141
	s_add_i32 m0, s6, 0x2000
	s_add_u32 s38, s68, 0x20000
	global_load_lds_dwordx4 v128, s[68:69]
	s_addc_u32 s39, s69, 0
	v_mov_b32_e32 v128, v139
	s_add_i32 s6, s95, s86
	s_mov_b32 m0, s6
	s_nop 0
	global_load_lds_dwordx4 v128, s[38:39]
	v_mov_b32_e32 v128, v141
	s_add_i32 m0, s6, 0x2000
	s_nop 0
	global_load_lds_dwordx4 v128, s[38:39]
	v_mov_b32_e32 v128, v138
	s_mov_b32 m0, s87
	s_nop 0
	global_load_lds_dwordx4 v128, s[66:67]
	v_mov_b32_e32 v128, v140
	s_mov_b32 m0, s88
	s_nop 0
	global_load_lds_dwordx4 v128, s[66:67]
	s_waitcnt vmcnt(8)
	s_waitcnt lgkmcnt(0)
	s_setprio 1
	s_barrier
	v_mfma_scale_f32_16x16x128_f8f6f4 v[64:67], v[130:137], v[68:75], v[64:67], v146, v146 op_sel_hi:[0,0,0]
	v_mfma_scale_f32_16x16x128_f8f6f4 v[44:47], v[156:163], v[68:75], v[44:47], v146, v146 op_sel_hi:[0,0,0]
	v_mfma_scale_f32_16x16x128_f8f6f4 v[56:59], v[148:155], v[68:75], v[56:59], v146, v146 op_sel_hi:[0,0,0]
	v_mfma_scale_f32_16x16x128_f8f6f4 v[52:55], v[130:137], v[76:83], v[52:55], v146, v146 op_sel_hi:[0,0,0]
	v_mfma_scale_f32_16x16x128_f8f6f4 v[48:51], v[148:155], v[76:83], v[48:51], v146, v146 op_sel_hi:[0,0,0]
	v_mfma_scale_f32_16x16x128_f8f6f4 v[40:43], v[130:137], v[84:91], v[40:43], v146, v146 op_sel_hi:[0,0,0]
	v_mfma_scale_f32_16x16x128_f8f6f4 v[196:199], v[164:171], v[68:75], v[36:39], v146, v146 op_sel_hi:[0,0,0]
	v_mfma_scale_f32_16x16x128_f8f6f4 v[200:203], v[156:163], v[76:83], v[28:31], v146, v146 op_sel_hi:[0,0,0]
	v_mfma_scale_f32_16x16x128_f8f6f4 v[212:215], v[164:171], v[76:83], v[20:23], v146, v146 op_sel_hi:[0,0,0]
	v_mfma_scale_f32_16x16x128_f8f6f4 v[216:219], v[156:163], v[84:91], v[12:15], v146, v146 op_sel_hi:[0,0,0]
	v_mfma_scale_f32_16x16x128_f8f6f4 v[220:223], v[148:155], v[84:91], v[32:35], v146, v146 op_sel_hi:[0,0,0]
	v_mfma_scale_f32_16x16x128_f8f6f4 v[224:227], v[164:171], v[84:91], v[8:11], v146, v146 op_sel_hi:[0,0,0]
	v_mfma_scale_f32_16x16x128_f8f6f4 v[228:231], v[130:137], v[92:99], v[24:27], v146, v146 op_sel_hi:[0,0,0]
	v_mfma_scale_f32_16x16x128_f8f6f4 v[232:235], v[156:163], v[92:99], v[4:7], v146, v146 op_sel_hi:[0,0,0]
	v_mfma_scale_f32_16x16x128_f8f6f4 v[236:239], v[148:155], v[92:99], v[16:19], v146, v146 op_sel_hi:[0,0,0]
	v_mfma_scale_f32_16x16x128_f8f6f4 v[240:243], v[164:171], v[92:99], v[0:3], v146, v146 op_sel_hi:[0,0,0]
	s_barrier
; #define PG8_LDA(dst, b, h) do { if constexpr (FP8) { _Pragma("unroll") for (int m = 0; m < 4; ++m) dst##8[m] = PG8_LD8(PG8_SA(b, h), aoff, aoff1, m); } \
;         else { _Pragma("unroll") for (int m = 0; m < 4; ++m) _Pragma("unroll") for (int k = 0; k < 2; ++k) dst[m][k] = *(const LAS bf16x8*)(lds + PG8_SA(b, h) + (k ? aoff1 : aoff) + m * 2048); } } while (0)
; #define PG8_LDB(dst, b, h) do { if constexpr (FP8) { dst##8[0] = PG8_LD8(PG8_SB(b, h), boff, boff1, 0); dst##8[1] = PG8_LD8(PG8_SB(b, h), boff, boff1, 1); } \
;         else { _Pragma("unroll") for (int n = 0; n < 2; ++n) _Pragma("unroll") for (int k = 0; k < 2; ++k) dst[n][k] = *(const LAS bf16x8*)(lds + PG8_SB(b, h) + (k ? boff1 : boff) + n * 2048); } } while (0)
; #define PG8_WAIT_V(n) asm volatile("s_waitcnt vmcnt(" #n ")" ::: "memory")
; #define PG8_WAIT_L(n) asm volatile("s_waitcnt lgkmcnt(" #n ")" ::: "memory")
; #define PG8_BAR __builtin_amdgcn_s_barrier()
; #define PG8_SCHED __builtin_amdgcn_sched_barrier(0)
; #define PG8_S3 PG8_STAGE(PG8_SA(0, 1), a2 + hstepA, voffA)
; #define PG8_S4 do { PG8_STAGE(PG8_SB(1, 0), b3, voffB); PG8_STAGE(PG8_SB(1, 1), b3 + hstepB, voffB); PG8_STAGE(PG8_SA(1, 0), a3, voffA); } while (0)
; template <class Epi, class SchedT, bool ALIGN_EPI, bool SP2, bool FP8 = false>
; __device__ __forceinline__ void gemm_phase(LAS unsigned char* lds, const Gemm g, const SchedT& S, const Epi& E, const int wid) {
;     ...
;             PG8_WAIT_V(8); PG8_WAIT_L(0); PG8_BAR; PG8_MMAP(1, 0, 1); PG8_BAR; PG8_SCHED;
;             PG8_LDB(B0, 1, 0); PG8_LDB(B1, 1, 1); PG8_SCHED; PG8_LDA(At, 1, 0); PG8_S3;
;             PG8_WAIT_V(8); PG8_WAIT_L(0); PG8_BAR; PG8_MMAP(0, 1, 0); PG8_BAR; PG8_SCHED;
;             PG8_LDA(At, 1, 1); PG8_S4;
	s_setprio 0
	s_add_i32 s6, 0, 0x18000
	v_add_u32_e32 v8, s6, v142
	s_add_i32 s7, 0, 0x1c000
	s_nop 1
	ds_read_b128 v[0:3], v8
	ds_read_b128 v[4:7], v8 offset:16
	ds_read_b128 v[130:133], v8 offset:2048
	ds_read_b128 v[134:137], v8 offset:2064
	v_add_u32_e32 v8, s7, v142
	ds_read_b128 v[148:151], v8
	ds_read_b128 v[152:155], v8 offset:16
	ds_read_b128 v[156:159], v8 offset:2048
	ds_read_b128 v[160:163], v8 offset:2064
	s_add_u32 s38, s66, 0x90000
	v_mov_b32_e32 v68, v138
	s_mov_b32 m0, s89
	ds_read_b128 v[8:11], v145 offset:32768
	ds_read_b128 v[12:15], v145 offset:32784
	ds_read_b128 v[16:19], v145 offset:34816
	ds_read_b128 v[20:23], v145 offset:34832
	ds_read_b128 v[24:27], v145 offset:36864
	ds_read_b128 v[28:31], v145 offset:36880
	ds_read_b128 v[32:35], v145 offset:38912
	ds_read_b128 v[36:39], v145 offset:38928
	s_addc_u32 s39, s67, 0
	s_nop 0
	global_load_lds_dwordx4 v68, s[38:39]
	v_mov_b32_e32 v68, v140
	s_mov_b32 m0, s90
	s_nop 0
	global_load_lds_dwordx4 v68, s[38:39]
	s_waitcnt vmcnt(8)
	s_waitcnt lgkmcnt(0)
	s_setprio 1
	s_barrier
	v_mfma_scale_f32_16x16x128_f8f6f4 v[124:127], v[0:7], v[8:15], v[124:127], v146, v146 op_sel_hi:[0,0,0]
	v_mfma_scale_f32_16x16x128_f8f6f4 v[108:111], v[148:155], v[8:15], v[108:111], v146, v146 op_sel_hi:[0,0,0]
	v_mfma_scale_f32_16x16x128_f8f6f4 v[120:123], v[130:137], v[8:15], v[120:123], v146, v146 op_sel_hi:[0,0,0]
	v_mfma_scale_f32_16x16x128_f8f6f4 v[100:103], v[156:163], v[8:15], v[100:103], v146, v146 op_sel_hi:[0,0,0]
	v_mfma_scale_f32_16x16x128_f8f6f4 v[116:119], v[0:7], v[16:23], v[116:119], v146, v146 op_sel_hi:[0,0,0]
	v_mfma_scale_f32_16x16x128_f8f6f4 v[92:95], v[148:155], v[16:23], v[172:175], v146, v146 op_sel_hi:[0,0,0]
	v_mfma_scale_f32_16x16x128_f8f6f4 v[112:115], v[130:137], v[16:23], v[112:115], v146, v146 op_sel_hi:[0,0,0]
	v_mfma_scale_f32_16x16x128_f8f6f4 v[84:87], v[156:163], v[16:23], v[176:179], v146, v146 op_sel_hi:[0,0,0]
	v_mfma_scale_f32_16x16x128_f8f6f4 v[104:107], v[0:7], v[24:31], v[104:107], v146, v146 op_sel_hi:[0,0,0]
	v_mfma_scale_f32_16x16x128_f8f6f4 v[76:79], v[148:155], v[24:31], v[180:183], v146, v146 op_sel_hi:[0,0,0]
	v_mfma_scale_f32_16x16x128_f8f6f4 v[96:99], v[130:137], v[24:31], v[184:187], v146, v146 op_sel_hi:[0,0,0]
	v_mfma_scale_f32_16x16x128_f8f6f4 v[72:75], v[156:163], v[24:31], v[188:191], v146, v146 op_sel_hi:[0,0,0]
	v_mfma_scale_f32_16x16x128_f8f6f4 v[88:91], v[0:7], v[32:39], v[192:195], v146, v146 op_sel_hi:[0,0,0]
	v_mfma_scale_f32_16x16x128_f8f6f4 v[68:71], v[148:155], v[32:39], v[204:207], v146, v146 op_sel_hi:[0,0,0]
	v_mfma_scale_f32_16x16x128_f8f6f4 v[80:83], v[130:137], v[32:39], v[208:211], v146, v146 op_sel_hi:[0,0,0]
	v_mfma_scale_f32_16x16x128_f8f6f4 v[60:63], v[156:163], v[32:39], v[60:63], v146, v146 op_sel_hi:[0,0,0]
	s_barrier
	s_setprio 0
	v_mov_b32_e32 v128, v139
	ds_read_b128 v[8:11], v145 offset:49152
	ds_read_b128 v[12:15], v145 offset:49168
	ds_read_b128 v[16:19], v145 offset:51200
	ds_read_b128 v[20:23], v145 offset:51216
	ds_read_b128 v[164:167], v145 offset:53248
	ds_read_b128 v[168:171], v145 offset:53264
	ds_read_b128 v[172:175], v145 offset:55296
	ds_read_b128 v[176:179], v145 offset:55312
	s_add_i32 s6, s6, s86
	v_lshl_add_u64 v[24:25], s[68:69], 0, v[128:129]
	v_lshl_add_u64 v[24:25], v[24:25], 0, s[40:41]
	s_mov_b32 m0, s6
	v_mov_b32_e32 v128, v141
	global_load_lds_dwordx4 v[24:25], off
	s_add_i32 m0, s6, 0x2000
	v_lshl_add_u64 v[24:25], s[68:69], 0, v[128:129]
	v_lshl_add_u64 v[24:25], v[24:25], 0, s[40:41]
	s_add_u32 s38, s68, 0x20080
	global_load_lds_dwordx4 v[24:25], off
	s_addc_u32 s39, s69, 0
	v_mov_b32_e32 v24, v139
	s_add_i32 s6, s7, s86
	s_mov_b32 m0, s6
	v_mov_b32_e32 v128, v138
	global_load_lds_dwordx4 v24, s[38:39]
	v_mov_b32_e32 v24, v141
	s_add_i32 m0, s6, 0x2000
	s_nop 0
	global_load_lds_dwordx4 v24, s[38:39]
	s_mov_b32 m0, s92
	v_lshl_add_u64 v[24:25], s[66:67], 0, v[128:129]
	v_lshl_add_u64 v[24:25], v[24:25], 0, s[40:41]
	v_mov_b32_e32 v128, v140
	global_load_lds_dwordx4 v[24:25], off
	s_mov_b32 m0, s93
	v_lshl_add_u64 v[24:25], s[66:67], 0, v[128:129]
	v_lshl_add_u64 v[24:25], v[24:25], 0, s[40:41]
	global_load_lds_dwordx4 v[24:25], off
	s_waitcnt vmcnt(8)
	s_waitcnt lgkmcnt(0)
	s_setprio 1
	s_barrier
; #define PG8_WAIT_V(n) asm volatile("s_waitcnt vmcnt(" #n ")" ::: "memory")
; #define PG8_WAIT_L(n) asm volatile("s_waitcnt lgkmcnt(" #n ")" ::: "memory")
;     __device__ __forceinline__ void operator()(const f32x4 (&acc)[2][2][4][2], const Unit& u, int wr, int wc, int fr, int fq) const {
;     ...
;             for (int m = 0; m < 4; ++m) { bf16_t* rowp = O + (size_t)(row0 + ai * HALF + m * 16) * ldc + col0;
; #pragma unroll
;                 for (int bj = 0; bj < 2; ++bj) { const f32x4 v0 = acc[ai][bj][m][0] * sc, v1 = acc[ai][bj][m][1] * sc;
;                     u32x4 w; w.x = pk2(v0[0], v0[1]); w.y = pk2(v0[2], v0[3]); w.z = pk2(v1[0], v1[1]); w.w = pk2(v1[2], v1[3]);
;                     *(u32x4*)(rowp + bj * HALF) = w; } }
; template <class Epi, class SchedT, bool ALIGN_EPI, bool SP2, bool FP8 = false>
; __device__ __forceinline__ void gemm_phase(LAS unsigned char* lds, const Gemm g, const SchedT& S, const Epi& E, const int wid) {
;     ...
;             PG8_WAIT_V(8); PG8_WAIT_L(0); PG8_BAR; PG8_MMAP(1, 1, 1); PG8_BAR; PG8_SCHED;
;             } else {
;             PG8_LDB(B0, 0, 0); PG8_SCHED; PG8_LDA(At, 0, 0); PG8_STAGE(PG8_SA(1, 1), a1 + hstepA, voffA);
;             PG8_WAIT_L(8); PG8_BAR; PG8_WAIT_L(0); PG8_MMA(0, 0, At, B0); PG8_BAR; PG8_SCHED;
;             PG8_LDB(B1, 0, 1); PG8_STAGE(PG8_SB(0, 0), b2, voffB);
;             PG8_BAR; PG8_WAIT_L(0); PG8_MMA(0, 1, At, B1); PG8_BAR;
;             PG8_LDA(At, 0, 1); PG8_STAGE(PG8_SA(0, 0), a2, voffA);
;             PG8_BAR; PG8_WAIT_L(0); PG8_MMA(1, 0, At, B0); PG8_BAR; PG8_SCHED;
;             PG8_STAGE(PG8_SB(0, 1), b2 + hstepB, voffB);
;             PG8_WAIT_V(6); PG8_BAR; PG8_MMA(1, 1, At, B1); PG8_BAR;
;             PG8_LDB(B0, 1, 0); PG8_SCHED; PG8_LDA(At, 1, 0); PG8_STAGE(PG8_SA(0, 1), a2 + hstepA, voffA);
;             PG8_WAIT_L(8); PG8_BAR; PG8_WAIT_L(0); PG8_MMA(0, 0, At, B0); PG8_BAR; PG8_SCHED;
;             PG8_LDB(B1, 1, 1); PG8_STAGE(PG8_SB(1, 0), b3, voffB);
;             PG8_BAR; PG8_WAIT_L(0); PG8_MMA(0, 1, At, B1); PG8_BAR;
;             PG8_LDA(At, 1, 1); PG8_STAGE(PG8_SA(1, 0), a3, voffA);
;             PG8_BAR; PG8_WAIT_L(0); PG8_MMA(1, 0, At, B0); PG8_BAR; PG8_SCHED;
;             PG8_STAGE(PG8_SB(1, 1), b3 + hstepB, voffB);
;             PG8_WAIT_V(6); PG8_BAR; PG8_MMA(1, 1, At, B1); PG8_BAR;
;             }
;         }
;         if constexpr (ALIGN_EPI) { if (wr == 0) PG8_BAR; }
	v_mfma_scale_f32_16x16x128_f8f6f4 v[64:67], v[0:7], v[8:15], v[64:67], v146, v146 op_sel_hi:[0,0,0]
	v_mfma_scale_f32_16x16x128_f8f6f4 v[44:47], v[148:155], v[8:15], v[44:47], v146, v146 op_sel_hi:[0,0,0]
	v_mfma_scale_f32_16x16x128_f8f6f4 v[56:59], v[130:137], v[8:15], v[56:59], v146, v146 op_sel_hi:[0,0,0]
	v_mfma_scale_f32_16x16x128_f8f6f4 v[36:39], v[156:163], v[8:15], v[196:199], v146, v146 op_sel_hi:[0,0,0]
	v_mfma_scale_f32_16x16x128_f8f6f4 v[52:55], v[0:7], v[16:23], v[52:55], v146, v146 op_sel_hi:[0,0,0]
	v_mfma_scale_f32_16x16x128_f8f6f4 v[28:31], v[148:155], v[16:23], v[200:203], v146, v146 op_sel_hi:[0,0,0]
	v_mfma_scale_f32_16x16x128_f8f6f4 v[48:51], v[130:137], v[16:23], v[48:51], v146, v146 op_sel_hi:[0,0,0]
	v_mfma_scale_f32_16x16x128_f8f6f4 v[20:23], v[156:163], v[16:23], v[212:215], v146, v146 op_sel_hi:[0,0,0]
	v_mfma_scale_f32_16x16x128_f8f6f4 v[40:43], v[0:7], v[164:171], v[40:43], v146, v146 op_sel_hi:[0,0,0]
	v_mfma_scale_f32_16x16x128_f8f6f4 v[12:15], v[148:155], v[164:171], v[216:219], v146, v146 op_sel_hi:[0,0,0]
	v_mfma_scale_f32_16x16x128_f8f6f4 v[32:35], v[130:137], v[164:171], v[220:223], v146, v146 op_sel_hi:[0,0,0]
	v_mfma_scale_f32_16x16x128_f8f6f4 v[8:11], v[156:163], v[164:171], v[224:227], v146, v146 op_sel_hi:[0,0,0]
	v_mfma_scale_f32_16x16x128_f8f6f4 v[24:27], v[0:7], v[172:179], v[228:231], v146, v146 op_sel_hi:[0,0,0]
	v_mfma_scale_f32_16x16x128_f8f6f4 v[4:7], v[148:155], v[172:179], v[232:235], v146, v146 op_sel_hi:[0,0,0]
	v_mfma_scale_f32_16x16x128_f8f6f4 v[16:19], v[130:137], v[172:179], v[236:239], v146, v146 op_sel_hi:[0,0,0]
	v_mfma_scale_f32_16x16x128_f8f6f4 v[0:3], v[156:163], v[172:179], v[240:243], v146, v146 op_sel_hi:[0,0,0]
	s_barrier
	s_setprio 0
	s_add_u32 s52, s52, 0x100
	s_addc_u32 s53, s53, 0
	s_add_u32 s21, s21, 0x100
	s_addc_u32 s24, s24, 0
	s_cmp_ge_i32 s30, s22
	s_mov_b32 s31, s30
	s_cbranch_scc0 .LBB0_239
	v_pk_mul_f32 v[126:127], v[126:127], s[42:43] op_sel_hi:[1,0]
	v_pk_mul_f32 v[124:125], v[124:125], s[42:43] op_sel_hi:[1,0]
	v_pk_mul_f32 v[122:123], v[122:123], s[42:43] op_sel_hi:[1,0]
	v_pk_mul_f32 v[120:121], v[120:121], s[42:43] op_sel_hi:[1,0]
	v_pk_mul_f32 v[130:131], v[110:111], s[42:43] op_sel_hi:[1,0]
	v_pk_mul_f32 v[132:133], v[108:109], s[42:43] op_sel_hi:[1,0]
	v_pk_mul_f32 v[134:135], v[102:103], s[42:43] op_sel_hi:[1,0]
	v_pk_mul_f32 v[136:137], v[100:101], s[42:43] op_sel_hi:[1,0]
	v_pk_mul_f32 v[100:101], v[118:119], s[42:43] op_sel_hi:[1,0]
	v_pk_mul_f32 v[102:103], v[116:117], s[42:43] op_sel_hi:[1,0]
	v_pk_mul_f32 v[108:109], v[114:115], s[42:43] op_sel_hi:[1,0]
	v_pk_mul_f32 v[110:111], v[112:113], s[42:43] op_sel_hi:[1,0]
	v_pk_mul_f32 v[112:113], v[94:95], s[42:43] op_sel_hi:[1,0]
	v_pk_mul_f32 v[114:115], v[92:93], s[42:43] op_sel_hi:[1,0]
	v_pk_mul_f32 v[116:117], v[86:87], s[42:43] op_sel_hi:[1,0]
	v_pk_mul_f32 v[118:119], v[84:85], s[42:43] op_sel_hi:[1,0]
	v_pk_mul_f32 v[84:85], v[106:107], s[42:43] op_sel_hi:[1,0]
	v_pk_mul_f32 v[86:87], v[104:105], s[42:43] op_sel_hi:[1,0]
	v_pk_mul_f32 v[92:93], v[98:99], s[42:43] op_sel_hi:[1,0]
	v_pk_mul_f32 v[94:95], v[96:97], s[42:43] op_sel_hi:[1,0]
	v_pk_mul_f32 v[96:97], v[78:79], s[42:43] op_sel_hi:[1,0]
	v_pk_mul_f32 v[98:99], v[76:77], s[42:43] op_sel_hi:[1,0]
	v_pk_mul_f32 v[104:105], v[74:75], s[42:43] op_sel_hi:[1,0]
	v_pk_mul_f32 v[106:107], v[72:73], s[42:43] op_sel_hi:[1,0]
	v_pk_mul_f32 v[72:73], v[90:91], s[42:43] op_sel_hi:[1,0]
	v_pk_mul_f32 v[74:75], v[88:89], s[42:43] op_sel_hi:[1,0]
	v_pk_mul_f32 v[76:77], v[82:83], s[42:43] op_sel_hi:[1,0]
	v_pk_mul_f32 v[78:79], v[80:81], s[42:43] op_sel_hi:[1,0]
	v_pk_mul_f32 v[70:71], v[70:71], s[42:43] op_sel_hi:[1,0]
	v_pk_mul_f32 v[68:69], v[68:69], s[42:43] op_sel_hi:[1,0]
	v_pk_mul_f32 v[62:63], v[62:63], s[42:43] op_sel_hi:[1,0]
	v_pk_mul_f32 v[80:81], v[60:61], s[42:43] op_sel_hi:[1,0]
	v_pk_mul_f32 v[60:61], v[66:67], s[42:43] op_sel_hi:[1,0]
	v_pk_mul_f32 v[64:65], v[64:65], s[42:43] op_sel_hi:[1,0]
	v_pk_mul_f32 v[58:59], v[58:59], s[42:43] op_sel_hi:[1,0]
	v_pk_mul_f32 v[56:57], v[56:57], s[42:43] op_sel_hi:[1,0]
	v_pk_mul_f32 v[66:67], v[46:47], s[42:43] op_sel_hi:[1,0]
	v_pk_mul_f32 v[82:83], v[44:45], s[42:43] op_sel_hi:[1,0]
	v_pk_mul_f32 v[88:89], v[38:39], s[42:43] op_sel_hi:[1,0]
	v_pk_mul_f32 v[90:91], v[36:37], s[42:43] op_sel_hi:[1,0]
	v_pk_mul_f32 v[36:37], v[54:55], s[42:43] op_sel_hi:[1,0]
	v_pk_mul_f32 v[38:39], v[52:53], s[42:43] op_sel_hi:[1,0]
	v_pk_mul_f32 v[44:45], v[50:51], s[42:43] op_sel_hi:[1,0]
	v_pk_mul_f32 v[46:47], v[48:49], s[42:43] op_sel_hi:[1,0]
	v_pk_mul_f32 v[48:49], v[30:31], s[42:43] op_sel_hi:[1,0]
	v_pk_mul_f32 v[50:51], v[28:29], s[42:43] op_sel_hi:[1,0]
	v_pk_mul_f32 v[52:53], v[22:23], s[42:43] op_sel_hi:[1,0]
	v_pk_mul_f32 v[54:55], v[20:21], s[42:43] op_sel_hi:[1,0]
	v_pk_mul_f32 v[20:21], v[42:43], s[42:43] op_sel_hi:[1,0]
	v_pk_mul_f32 v[22:23], v[40:41], s[42:43] op_sel_hi:[1,0]
	v_pk_mul_f32 v[28:29], v[34:35], s[42:43] op_sel_hi:[1,0]
	v_pk_mul_f32 v[30:31], v[32:33], s[42:43] op_sel_hi:[1,0]
	v_pk_mul_f32 v[32:33], v[14:15], s[42:43] op_sel_hi:[1,0]
	v_pk_mul_f32 v[34:35], v[12:13], s[42:43] op_sel_hi:[1,0]
	v_pk_mul_f32 v[40:41], v[10:11], s[42:43] op_sel_hi:[1,0]
	v_pk_mul_f32 v[42:43], v[8:9], s[42:43] op_sel_hi:[1,0]
	v_pk_mul_f32 v[8:9], v[26:27], s[42:43] op_sel_hi:[1,0]
	v_pk_mul_f32 v[10:11], v[24:25], s[42:43] op_sel_hi:[1,0]
	v_pk_mul_f32 v[12:13], v[18:19], s[42:43] op_sel_hi:[1,0]
	v_pk_mul_f32 v[14:15], v[16:17], s[42:43] op_sel_hi:[1,0]
	v_pk_mul_f32 v[6:7], v[6:7], s[42:43] op_sel_hi:[1,0]
	v_pk_mul_f32 v[4:5], v[4:5], s[42:43] op_sel_hi:[1,0]
	v_pk_mul_f32 v[2:3], v[2:3], s[42:43] op_sel_hi:[1,0]
	v_pk_mul_f32 v[0:1], v[0:1], s[42:43] op_sel_hi:[1,0]
	s_and_b64 vcc, exec, s[96:97]
	s_cbranch_vccz .LBB0_242

; #define PG8_LDA(dst, b, h) do { if constexpr (FP8) { _Pragma("unroll") for (int m = 0; m < 4; ++m) dst##8[m] = PG8_LD8(PG8_SA(b, h), aoff, aoff1, m); } \
;         else { _Pragma("unroll") for (int m = 0; m < 4; ++m) _Pragma("unroll") for (int k = 0; k < 2; ++k) dst[m][k] = *(const LAS bf16x8*)(lds + PG8_SA(b, h) + (k ? aoff1 : aoff) + m * 2048); } } while (0)
; #define PG8_LDB(dst, b, h) do { if constexpr (FP8) { dst##8[0] = PG8_LD8(PG8_SB(b, h), boff, boff1, 0); dst##8[1] = PG8_LD8(PG8_SB(b, h), boff, boff1, 1); } \
;         else { _Pragma("unroll") for (int n = 0; n < 2; ++n) _Pragma("unroll") for (int k = 0; k < 2; ++k) dst[n][k] = *(const LAS bf16x8*)(lds + PG8_SB(b, h) + (k ? boff1 : boff) + n * 2048); } } while (0)
; #define PG8_WAIT_V(n) asm volatile("s_waitcnt vmcnt(" #n ")" ::: "memory")
; #define PG8_WAIT_L(n) asm volatile("s_waitcnt lgkmcnt(" #n ")" ::: "memory")
; #define PG8_BAR __builtin_amdgcn_s_barrier()
; #define PG8_SCHED __builtin_amdgcn_sched_barrier(0)
; #define PG8_S1 PG8_STAGE(PG8_SA(1, 1), a1 + hstepA, voffA)
; #define PG8_S2 do { PG8_STAGE(PG8_SB(0, 0), b2, voffB); PG8_STAGE(PG8_SB(0, 1), b2 + hstepB, voffB); PG8_STAGE(PG8_SA(0, 0), a2, voffA); } while (0)
; template <class Epi, class SchedT, bool ALIGN_EPI, bool SP2, bool FP8 = false>
; __device__ __forceinline__ void gemm_phase(LAS unsigned char* lds, const Gemm g, const SchedT& S, const Epi& E, const int wid) {
;     ...
;             PG8_LDB(B0, 0, 0); PG8_LDB(B1, 0, 1); PG8_SCHED; PG8_LDA(At, 0, 0); PG8_S1;
;             PG8_WAIT_V(8); PG8_WAIT_L(0); PG8_BAR; PG8_MMAP(0, 0, 0); PG8_BAR; PG8_SCHED;
;             PG8_LDA(At, 0, 1); PG8_S2;
;             PG8_WAIT_V(8); PG8_WAIT_L(0); PG8_BAR; PG8_MMAP(1, 0, 1); PG8_BAR; PG8_SCHED;
.LBB0_256:
	ds_read_b128 v[146:149], v139
	ds_read_b128 v[150:153], v139 offset:1024
	ds_read_b128 v[154:157], v140
	ds_read_b128 v[158:161], v140 offset:1024
	ds_read_b128 v[162:165], v141
	ds_read_b128 v[166:169], v141 offset:1024
	ds_read_b128 v[170:173], v142
	ds_read_b128 v[174:177], v142 offset:1024
	s_add_i32 s43, s39, 2
	s_add_u32 s6, s50, 0xfffc0080
	s_addc_u32 s7, s51, -1
	s_cmp_eq_u32 s30, s39
	s_cselect_b32 s53, s9, s7
	s_cselect_b32 s52, s20, s6
	s_cselect_b32 s67, s21, s38
	s_cselect_b32 s66, s24, s31
	v_mov_b32_e32 v128, v134
	ds_read_b128 v[178:181], v143
	ds_read_b128 v[182:185], v143 offset:1024
	ds_read_b128 v[186:189], v143 offset:2048
	ds_read_b128 v[190:193], v143 offset:3072
	ds_read_b128 v[194:197], v143 offset:4096
	ds_read_b128 v[198:201], v143 offset:5120
	ds_read_b128 v[202:205], v143 offset:6144
	ds_read_b128 v[206:209], v143 offset:7168
	s_add_i32 m0, s87, 0xc000
	s_nop 0
	global_load_lds_dwordx4 v128, s[50:51]
	v_mov_b32_e32 v128, v136
	s_add_i32 m0, s87, 0xe000
	s_nop 0
	global_load_lds_dwordx4 v128, s[50:51]
	s_waitcnt vmcnt(8)
	s_waitcnt lgkmcnt(0)
	s_setprio 1
	s_barrier
	v_mfma_f32_16x16x32_bf16 v[124:127], v[146:149], v[178:181], v[124:127]
	v_mfma_f32_16x16x32_bf16 v[120:123], v[154:157], v[178:181], v[120:123]
	v_mfma_f32_16x16x32_bf16 v[104:107], v[154:157], v[186:189], v[104:107]
	v_mfma_f32_16x16x32_bf16 v[108:111], v[146:149], v[186:189], v[108:111]
	v_mfma_f32_16x16x32_bf16 v[92:95], v[146:149], v[194:197], v[92:95]
	v_mfma_f32_16x16x32_bf16 v[88:91], v[154:157], v[194:197], v[88:91]
	v_mfma_f32_16x16x32_bf16 v[72:75], v[154:157], v[202:205], v[72:75]
	v_mfma_f32_16x16x32_bf16 v[76:79], v[146:149], v[202:205], v[76:79]
	v_mfma_f32_16x16x32_bf16 v[124:127], v[150:153], v[182:185], v[124:127]
	v_mfma_f32_16x16x32_bf16 v[120:123], v[158:161], v[182:185], v[120:123]
	v_mfma_f32_16x16x32_bf16 v[104:107], v[158:161], v[190:193], v[104:107]
	v_mfma_f32_16x16x32_bf16 v[108:111], v[150:153], v[190:193], v[108:111]
	v_mfma_f32_16x16x32_bf16 v[92:95], v[150:153], v[198:201], v[92:95]
	v_mfma_f32_16x16x32_bf16 v[88:91], v[158:161], v[198:201], v[88:91]
	v_mfma_f32_16x16x32_bf16 v[72:75], v[158:161], v[206:209], v[72:75]
	v_mfma_f32_16x16x32_bf16 v[76:79], v[150:153], v[206:209], v[76:79]
	s_setprio 0
	s_setprio 1
	v_mfma_f32_16x16x32_bf16 v[116:119], v[162:165], v[178:181], v[116:119]
	v_mfma_f32_16x16x32_bf16 v[112:115], v[170:173], v[178:181], v[112:115]
	v_mfma_f32_16x16x32_bf16 v[96:99], v[170:173], v[186:189], v[96:99]
	v_mfma_f32_16x16x32_bf16 v[100:103], v[162:165], v[186:189], v[100:103]
	v_mfma_f32_16x16x32_bf16 v[84:87], v[162:165], v[194:197], v[84:87]
	v_mfma_f32_16x16x32_bf16 v[80:83], v[170:173], v[194:197], v[80:83]
	v_mfma_f32_16x16x32_bf16 v[56:59], v[170:173], v[202:205], v[56:59]
	v_mfma_f32_16x16x32_bf16 v[60:63], v[162:165], v[202:205], v[60:63]
	v_mfma_f32_16x16x32_bf16 v[116:119], v[166:169], v[182:185], v[116:119]
	v_mfma_f32_16x16x32_bf16 v[112:115], v[174:177], v[182:185], v[112:115]
	v_mfma_f32_16x16x32_bf16 v[96:99], v[174:177], v[190:193], v[96:99]
	v_mfma_f32_16x16x32_bf16 v[100:103], v[166:169], v[190:193], v[100:103]
	v_mfma_f32_16x16x32_bf16 v[84:87], v[166:169], v[198:201], v[84:87]
	v_mfma_f32_16x16x32_bf16 v[80:83], v[174:177], v[198:201], v[80:83]
	v_mfma_f32_16x16x32_bf16 v[56:59], v[174:177], v[206:209], v[56:59]
	v_mfma_f32_16x16x32_bf16 v[60:63], v[166:169], v[206:209], v[60:63]
	s_barrier
	s_setprio 0
	v_mov_b32_e32 v128, v135
	s_add_i32 s6, s94, s86
	ds_read_b128 v[178:181], v143 offset:16384
	ds_read_b128 v[182:185], v143 offset:17408
	ds_read_b128 v[186:189], v143 offset:18432
	ds_read_b128 v[190:193], v143 offset:19456
	ds_read_b128 v[194:197], v143 offset:20480
	ds_read_b128 v[198:201], v143 offset:21504
	ds_read_b128 v[202:205], v143 offset:22528
	ds_read_b128 v[206:209], v143 offset:23552
	s_mov_b32 m0, s6
	s_nop 0
	global_load_lds_dwordx4 v128, s[66:67]
	v_mov_b32_e32 v128, v137
	s_add_i32 m0, s6, 0x2000
	s_add_u32 s60, s66, 0x40000
	global_load_lds_dwordx4 v128, s[66:67]
	s_addc_u32 s61, s67, 0
	v_mov_b32_e32 v128, v135
	s_add_i32 s6, s95, s86
	s_mov_b32 m0, s6
	s_nop 0
	global_load_lds_dwordx4 v128, s[60:61]
	v_mov_b32_e32 v128, v137
	s_add_i32 m0, s6, 0x2000
	s_nop 0
	global_load_lds_dwordx4 v128, s[60:61]
	v_mov_b32_e32 v128, v134
	s_mov_b32 m0, s87
	s_nop 0
	global_load_lds_dwordx4 v128, s[52:53]
	v_mov_b32_e32 v128, v136
	s_mov_b32 m0, s88
	s_nop 0
	global_load_lds_dwordx4 v128, s[52:53]
	s_waitcnt vmcnt(8)
	s_waitcnt lgkmcnt(0)
	s_setprio 1
	s_barrier
	v_mfma_f32_16x16x32_bf16 v[68:71], v[146:149], v[178:181], v[68:71]
	v_mfma_f32_16x16x32_bf16 v[64:67], v[154:157], v[178:181], v[64:67]
	v_mfma_f32_16x16x32_bf16 v[40:43], v[154:157], v[186:189], v[40:43]
	v_mfma_f32_16x16x32_bf16 v[44:47], v[146:149], v[186:189], v[44:47]
	v_mfma_f32_16x16x32_bf16 v[28:31], v[146:149], v[194:197], v[28:31]
	v_mfma_f32_16x16x32_bf16 v[24:27], v[154:157], v[194:197], v[24:27]
	v_mfma_f32_16x16x32_bf16 v[8:11], v[154:157], v[202:205], v[8:11]
	v_mfma_f32_16x16x32_bf16 v[12:15], v[146:149], v[202:205], v[12:15]
	v_mfma_f32_16x16x32_bf16 v[68:71], v[150:153], v[182:185], v[68:71]
	v_mfma_f32_16x16x32_bf16 v[64:67], v[158:161], v[182:185], v[64:67]
	v_mfma_f32_16x16x32_bf16 v[40:43], v[158:161], v[190:193], v[40:43]
	v_mfma_f32_16x16x32_bf16 v[44:47], v[150:153], v[190:193], v[44:47]
	v_mfma_f32_16x16x32_bf16 v[28:31], v[150:153], v[198:201], v[28:31]
	v_mfma_f32_16x16x32_bf16 v[24:27], v[158:161], v[198:201], v[24:27]
	v_mfma_f32_16x16x32_bf16 v[8:11], v[158:161], v[206:209], v[8:11]
	v_mfma_f32_16x16x32_bf16 v[12:15], v[150:153], v[206:209], v[12:15]
	s_setprio 0
	s_setprio 1
	v_mfma_f32_16x16x32_bf16 v[52:55], v[162:165], v[178:181], v[52:55]
	v_mfma_f32_16x16x32_bf16 v[48:51], v[170:173], v[178:181], v[48:51]
	v_mfma_f32_16x16x32_bf16 v[32:35], v[170:173], v[186:189], v[32:35]
	v_mfma_f32_16x16x32_bf16 v[36:39], v[162:165], v[186:189], v[36:39]
	v_mfma_f32_16x16x32_bf16 v[20:23], v[162:165], v[194:197], v[20:23]
	v_mfma_f32_16x16x32_bf16 v[16:19], v[170:173], v[194:197], v[16:19]
	v_mfma_f32_16x16x32_bf16 v[0:3], v[170:173], v[202:205], v[0:3]
	v_mfma_f32_16x16x32_bf16 v[4:7], v[162:165], v[202:205], v[4:7]
	v_mfma_f32_16x16x32_bf16 v[52:55], v[166:169], v[182:185], v[52:55]
	v_mfma_f32_16x16x32_bf16 v[48:51], v[174:177], v[182:185], v[48:51]
	v_mfma_f32_16x16x32_bf16 v[32:35], v[174:177], v[190:193], v[32:35]
	v_mfma_f32_16x16x32_bf16 v[36:39], v[166:169], v[190:193], v[36:39]
	v_mfma_f32_16x16x32_bf16 v[20:23], v[166:169], v[198:201], v[20:23]
	v_mfma_f32_16x16x32_bf16 v[16:19], v[174:177], v[198:201], v[16:19]
	v_mfma_f32_16x16x32_bf16 v[0:3], v[174:177], v[206:209], v[0:3]
	v_mfma_f32_16x16x32_bf16 v[4:7], v[166:169], v[206:209], v[4:7]
	s_barrier
; #define PG8_LDA(dst, b, h) do { if constexpr (FP8) { _Pragma("unroll") for (int m = 0; m < 4; ++m) dst##8[m] = PG8_LD8(PG8_SA(b, h), aoff, aoff1, m); } \
;         else { _Pragma("unroll") for (int m = 0; m < 4; ++m) _Pragma("unroll") for (int k = 0; k < 2; ++k) dst[m][k] = *(const LAS bf16x8*)(lds + PG8_SA(b, h) + (k ? aoff1 : aoff) + m * 2048); } } while (0)
; #define PG8_LDB(dst, b, h) do { if constexpr (FP8) { dst##8[0] = PG8_LD8(PG8_SB(b, h), boff, boff1, 0); dst##8[1] = PG8_LD8(PG8_SB(b, h), boff, boff1, 1); } \
;         else { _Pragma("unroll") for (int n = 0; n < 2; ++n) _Pragma("unroll") for (int k = 0; k < 2; ++k) dst[n][k] = *(const LAS bf16x8*)(lds + PG8_SB(b, h) + (k ? boff1 : boff) + n * 2048); } } while (0)
; #define PG8_WAIT_V(n) asm volatile("s_waitcnt vmcnt(" #n ")" ::: "memory")
; #define PG8_WAIT_L(n) asm volatile("s_waitcnt lgkmcnt(" #n ")" ::: "memory")
; #define PG8_BAR __builtin_amdgcn_s_barrier()
; #define PG8_SCHED __builtin_amdgcn_sched_barrier(0)
; #define PG8_S3 PG8_STAGE(PG8_SA(0, 1), a2 + hstepA, voffA)
; template <class Epi, class SchedT, bool ALIGN_EPI, bool SP2, bool FP8 = false>
; __device__ __forceinline__ void gemm_phase(LAS unsigned char* lds, const Gemm g, const SchedT& S, const Epi& E, const int wid) {
;     ...
;             PG8_LDB(B0, 1, 0); PG8_LDB(B1, 1, 1); PG8_SCHED; PG8_LDA(At, 1, 0); PG8_S3;
;             PG8_WAIT_V(8); PG8_WAIT_L(0); PG8_BAR; PG8_MMAP(0, 1, 0); PG8_BAR; PG8_SCHED;
	s_setprio 0
	s_add_i32 s6, 0, 0x18000
	v_add_u32_e32 v128, s6, v138
	s_add_i32 s7, 0, 0x1c000
	ds_read_b128 v[146:149], v128
	ds_read_b128 v[150:153], v128 offset:1024
	ds_read_b128 v[154:157], v144
	ds_read_b128 v[158:161], v144 offset:1024
	v_add_u32_e32 v128, s7, v138
	ds_read_b128 v[162:165], v128
	ds_read_b128 v[166:169], v128 offset:1024
	ds_read_b128 v[170:173], v145
	ds_read_b128 v[174:177], v145 offset:1024
	s_add_u32 s60, s52, 0x40000
	v_mov_b32_e32 v128, v134
	s_mov_b32 m0, s89
	ds_read_b128 v[178:181], v143 offset:32768
	ds_read_b128 v[182:185], v143 offset:33792
	ds_read_b128 v[186:189], v143 offset:34816
	ds_read_b128 v[190:193], v143 offset:35840
	ds_read_b128 v[194:197], v143 offset:36864
	ds_read_b128 v[198:201], v143 offset:37888
	ds_read_b128 v[202:205], v143 offset:38912
	ds_read_b128 v[206:209], v143 offset:39936
	s_addc_u32 s61, s53, 0
	s_nop 0
	global_load_lds_dwordx4 v128, s[60:61]
	v_mov_b32_e32 v128, v136
	s_mov_b32 m0, s90
	s_nop 0
	global_load_lds_dwordx4 v128, s[60:61]
	s_waitcnt vmcnt(8)
	s_waitcnt lgkmcnt(0)
	s_setprio 1
	s_barrier
	v_mfma_f32_16x16x32_bf16 v[124:127], v[146:149], v[178:181], v[124:127]
	v_mfma_f32_16x16x32_bf16 v[120:123], v[154:157], v[178:181], v[120:123]
	v_mfma_f32_16x16x32_bf16 v[104:107], v[154:157], v[186:189], v[104:107]
	v_mfma_f32_16x16x32_bf16 v[108:111], v[146:149], v[186:189], v[108:111]
	v_mfma_f32_16x16x32_bf16 v[92:95], v[146:149], v[194:197], v[92:95]
	v_mfma_f32_16x16x32_bf16 v[88:91], v[154:157], v[194:197], v[88:91]
	v_mfma_f32_16x16x32_bf16 v[72:75], v[154:157], v[202:205], v[72:75]
	v_mfma_f32_16x16x32_bf16 v[76:79], v[146:149], v[202:205], v[76:79]
	v_mfma_f32_16x16x32_bf16 v[124:127], v[150:153], v[182:185], v[124:127]
	v_mfma_f32_16x16x32_bf16 v[120:123], v[158:161], v[182:185], v[120:123]
	v_mfma_f32_16x16x32_bf16 v[104:107], v[158:161], v[190:193], v[104:107]
	v_mfma_f32_16x16x32_bf16 v[108:111], v[150:153], v[190:193], v[108:111]
	v_mfma_f32_16x16x32_bf16 v[92:95], v[150:153], v[198:201], v[92:95]
	v_mfma_f32_16x16x32_bf16 v[88:91], v[158:161], v[198:201], v[88:91]
	v_mfma_f32_16x16x32_bf16 v[72:75], v[158:161], v[206:209], v[72:75]
	v_mfma_f32_16x16x32_bf16 v[76:79], v[150:153], v[206:209], v[76:79]
	s_setprio 0
	s_setprio 1
	v_mfma_f32_16x16x32_bf16 v[116:119], v[162:165], v[178:181], v[116:119]
	v_mfma_f32_16x16x32_bf16 v[112:115], v[170:173], v[178:181], v[112:115]
	v_mfma_f32_16x16x32_bf16 v[96:99], v[170:173], v[186:189], v[96:99]
	v_mfma_f32_16x16x32_bf16 v[100:103], v[162:165], v[186:189], v[100:103]
	v_mfma_f32_16x16x32_bf16 v[84:87], v[162:165], v[194:197], v[84:87]
	v_mfma_f32_16x16x32_bf16 v[80:83], v[170:173], v[194:197], v[80:83]
	v_mfma_f32_16x16x32_bf16 v[56:59], v[170:173], v[202:205], v[56:59]
	v_mfma_f32_16x16x32_bf16 v[60:63], v[162:165], v[202:205], v[60:63]
	v_mfma_f32_16x16x32_bf16 v[116:119], v[166:169], v[182:185], v[116:119]
	v_mfma_f32_16x16x32_bf16 v[112:115], v[174:177], v[182:185], v[112:115]
	v_mfma_f32_16x16x32_bf16 v[96:99], v[174:177], v[190:193], v[96:99]
	v_mfma_f32_16x16x32_bf16 v[100:103], v[166:169], v[190:193], v[100:103]
	v_mfma_f32_16x16x32_bf16 v[84:87], v[166:169], v[198:201], v[84:87]
	v_mfma_f32_16x16x32_bf16 v[80:83], v[174:177], v[198:201], v[80:83]
	v_mfma_f32_16x16x32_bf16 v[56:59], v[174:177], v[206:209], v[56:59]
	v_mfma_f32_16x16x32_bf16 v[60:63], v[166:169], v[206:209], v[60:63]
	s_barrier
; #define PG8_STAGE(bufoff, gbase, voff) do { _Pragma("unroll") for (int _i = 0; _i < 2; ++_i) { unsigned vo_ = (voff)[_i]; asm volatile("" : "+v"(vo_));     \
;         __builtin_amdgcn_global_load_lds((const unsigned*)((const char*)(gbase) + vo_), (LAS unsigned*)(lds + (bufoff) + ldsw + _i * 8192), 16, 0, 0); } } while (0)
; #define PG8_LDA(dst, b, h) do { if constexpr (FP8) { _Pragma("unroll") for (int m = 0; m < 4; ++m) dst##8[m] = PG8_LD8(PG8_SA(b, h), aoff, aoff1, m); } \
;         else { _Pragma("unroll") for (int m = 0; m < 4; ++m) _Pragma("unroll") for (int k = 0; k < 2; ++k) dst[m][k] = *(const LAS bf16x8*)(lds + PG8_SA(b, h) + (k ? aoff1 : aoff) + m * 2048); } } while (0)
; template <class Epi, class SchedT, bool ALIGN_EPI, bool SP2, bool FP8 = false>
; __device__ __forceinline__ void gemm_phase(LAS unsigned char* lds, const Gemm g, const SchedT& S, const Epi& E, const int wid) {
;     ...
;             PG8_LDA(At, 1, 1); PG8_S4;
;             PG8_WAIT_V(8); PG8_WAIT_L(0); PG8_BAR; PG8_MMAP(1, 1, 1); PG8_BAR; PG8_SCHED;
;             } else {
;             PG8_LDB(B0, 0, 0); PG8_SCHED; PG8_LDA(At, 0, 0); PG8_STAGE(PG8_SA(1, 1), a1 + hstepA, voffA);
;             PG8_WAIT_L(8); PG8_BAR; PG8_WAIT_L(0); PG8_MMA(0, 0, At, B0); PG8_BAR; PG8_SCHED;
;             PG8_LDB(B1, 0, 1); PG8_STAGE(PG8_SB(0, 0), b2, voffB);
;             PG8_BAR; PG8_WAIT_L(0); PG8_MMA(0, 1, At, B1); PG8_BAR;
;             PG8_LDA(At, 0, 1); PG8_STAGE(PG8_SA(0, 0), a2, voffA);
;             PG8_BAR; PG8_WAIT_L(0); PG8_MMA(1, 0, At, B0); PG8_BAR; PG8_SCHED;
;             PG8_STAGE(PG8_SB(0, 1), b2 + hstepB, voffB);
;             PG8_WAIT_V(6); PG8_BAR; PG8_MMA(1, 1, At, B1); PG8_BAR;
;             PG8_LDB(B0, 1, 0); PG8_SCHED; PG8_LDA(At, 1, 0); PG8_STAGE(PG8_SA(0, 1), a2 + hstepA, voffA);
;             PG8_WAIT_L(8); PG8_BAR; PG8_WAIT_L(0); PG8_MMA(0, 0, At, B0); PG8_BAR; PG8_SCHED;
;             PG8_LDB(B1, 1, 1); PG8_STAGE(PG8_SB(1, 0), b3, voffB);
;             PG8_BAR; PG8_WAIT_L(0); PG8_MMA(0, 1, At, B1); PG8_BAR;
;             PG8_LDA(At, 1, 1); PG8_STAGE(PG8_SA(1, 0), a3, voffA);
;             PG8_BAR; PG8_WAIT_L(0); PG8_MMA(1, 0, At, B0); PG8_BAR; PG8_SCHED;
;             PG8_STAGE(PG8_SB(1, 1), b3 + hstepB, voffB);
;             PG8_WAIT_V(6); PG8_BAR; PG8_MMA(1, 1, At, B1); PG8_BAR;
;             }
;         }
;         if constexpr (ALIGN_EPI) { if (wr == 0) PG8_BAR; }
	s_setprio 0
	v_mov_b32_e32 v128, v135
	ds_read_b128 v[178:181], v143 offset:49152
	ds_read_b128 v[182:185], v143 offset:50176
	ds_read_b128 v[186:189], v143 offset:51200
	ds_read_b128 v[190:193], v143 offset:52224
	ds_read_b128 v[194:197], v143 offset:53248
	ds_read_b128 v[198:201], v143 offset:54272
	ds_read_b128 v[202:205], v143 offset:55296
	ds_read_b128 v[206:209], v143 offset:56320
	s_add_i32 s6, s6, s86
	v_lshl_add_u64 v[210:211], s[66:67], 0, v[128:129]
	v_lshl_add_u64 v[210:211], v[210:211], 0, s[36:37]
	s_mov_b32 m0, s6
	v_mov_b32_e32 v128, v137
	global_load_lds_dwordx4 v[210:211], off
	s_add_i32 m0, s6, 0x2000
	s_add_u32 s60, s66, 0x40080
	v_lshl_add_u64 v[210:211], s[66:67], 0, v[128:129]
	v_lshl_add_u64 v[210:211], v[210:211], 0, s[36:37]
	s_addc_u32 s61, s67, 0
	v_mov_b32_e32 v128, v135
	s_add_i32 s6, s7, s86
	global_load_lds_dwordx4 v[210:211], off
	s_mov_b32 m0, s6
	s_nop 0
	global_load_lds_dwordx4 v128, s[60:61]
	v_mov_b32_e32 v128, v137
	s_add_i32 m0, s6, 0x2000
	s_nop 0
	global_load_lds_dwordx4 v128, s[60:61]
	v_mov_b32_e32 v128, v134
	s_mov_b32 m0, s92
	v_lshl_add_u64 v[210:211], s[52:53], 0, v[128:129]
	v_lshl_add_u64 v[210:211], v[210:211], 0, s[36:37]
	v_mov_b32_e32 v128, v136
	global_load_lds_dwordx4 v[210:211], off
	s_mov_b32 m0, s93
	v_lshl_add_u64 v[210:211], s[52:53], 0, v[128:129]
	v_lshl_add_u64 v[210:211], v[210:211], 0, s[36:37]
	global_load_lds_dwordx4 v[210:211], off
	s_waitcnt vmcnt(8)
	s_waitcnt lgkmcnt(0)
	s_setprio 1
	s_barrier
	v_mfma_f32_16x16x32_bf16 v[68:71], v[146:149], v[178:181], v[68:71]
	v_mfma_f32_16x16x32_bf16 v[64:67], v[154:157], v[178:181], v[64:67]
	v_mfma_f32_16x16x32_bf16 v[40:43], v[154:157], v[186:189], v[40:43]
	v_mfma_f32_16x16x32_bf16 v[44:47], v[146:149], v[186:189], v[44:47]
	v_mfma_f32_16x16x32_bf16 v[28:31], v[146:149], v[194:197], v[28:31]
	v_mfma_f32_16x16x32_bf16 v[24:27], v[154:157], v[194:197], v[24:27]
	v_mfma_f32_16x16x32_bf16 v[8:11], v[154:157], v[202:205], v[8:11]
	v_mfma_f32_16x16x32_bf16 v[12:15], v[146:149], v[202:205], v[12:15]
	v_mfma_f32_16x16x32_bf16 v[68:71], v[150:153], v[182:185], v[68:71]
	v_mfma_f32_16x16x32_bf16 v[64:67], v[158:161], v[182:185], v[64:67]
	v_mfma_f32_16x16x32_bf16 v[40:43], v[158:161], v[190:193], v[40:43]
	v_mfma_f32_16x16x32_bf16 v[44:47], v[150:153], v[190:193], v[44:47]
	v_mfma_f32_16x16x32_bf16 v[28:31], v[150:153], v[198:201], v[28:31]
	v_mfma_f32_16x16x32_bf16 v[24:27], v[158:161], v[198:201], v[24:27]
	v_mfma_f32_16x16x32_bf16 v[8:11], v[158:161], v[206:209], v[8:11]
	v_mfma_f32_16x16x32_bf16 v[12:15], v[150:153], v[206:209], v[12:15]
	s_setprio 0
	s_setprio 1
	v_mfma_f32_16x16x32_bf16 v[52:55], v[162:165], v[178:181], v[52:55]
	v_mfma_f32_16x16x32_bf16 v[48:51], v[170:173], v[178:181], v[48:51]
	v_mfma_f32_16x16x32_bf16 v[32:35], v[170:173], v[186:189], v[32:35]
	v_mfma_f32_16x16x32_bf16 v[36:39], v[162:165], v[186:189], v[36:39]
	v_mfma_f32_16x16x32_bf16 v[20:23], v[162:165], v[194:197], v[20:23]
	v_mfma_f32_16x16x32_bf16 v[16:19], v[170:173], v[194:197], v[16:19]
	v_mfma_f32_16x16x32_bf16 v[0:3], v[170:173], v[202:205], v[0:3]
	v_mfma_f32_16x16x32_bf16 v[4:7], v[162:165], v[202:205], v[4:7]
	v_mfma_f32_16x16x32_bf16 v[52:55], v[166:169], v[182:185], v[52:55]
	v_mfma_f32_16x16x32_bf16 v[48:51], v[174:177], v[182:185], v[48:51]
	v_mfma_f32_16x16x32_bf16 v[32:35], v[174:177], v[190:193], v[32:35]
	v_mfma_f32_16x16x32_bf16 v[36:39], v[166:169], v[190:193], v[36:39]
	v_mfma_f32_16x16x32_bf16 v[20:23], v[166:169], v[198:201], v[20:23]
	v_mfma_f32_16x16x32_bf16 v[16:19], v[174:177], v[198:201], v[16:19]
	v_mfma_f32_16x16x32_bf16 v[0:3], v[174:177], v[206:209], v[0:3]
	v_mfma_f32_16x16x32_bf16 v[4:7], v[166:169], v[206:209], v[4:7]
	s_barrier
	s_setprio 0
	s_add_u32 s50, s50, 0x100
	s_addc_u32 s51, s51, 0
	s_add_u32 s31, s31, 0x100
	s_addc_u32 s38, s38, 0
	s_cmp_ge_i32 s43, s8
	s_mov_b32 s39, s43
	s_cbranch_scc0 .LBB0_256
	s_and_b64 vcc, exec, s[96:97]
	s_cbranch_vccz .LBB0_259

; #define PG8_LDA(dst, b, h) do { if constexpr (FP8) { _Pragma("unroll") for (int m = 0; m < 4; ++m) dst##8[m] = PG8_LD8(PG8_SA(b, h), aoff, aoff1, m); } \
;         else { _Pragma("unroll") for (int m = 0; m < 4; ++m) _Pragma("unroll") for (int k = 0; k < 2; ++k) dst[m][k] = *(const LAS bf16x8*)(lds + PG8_SA(b, h) + (k ? aoff1 : aoff) + m * 2048); } } while (0)
; #define PG8_LDB(dst, b, h) do { if constexpr (FP8) { dst##8[0] = PG8_LD8(PG8_SB(b, h), boff, boff1, 0); dst##8[1] = PG8_LD8(PG8_SB(b, h), boff, boff1, 1); } \
;         else { _Pragma("unroll") for (int n = 0; n < 2; ++n) _Pragma("unroll") for (int k = 0; k < 2; ++k) dst[n][k] = *(const LAS bf16x8*)(lds + PG8_SB(b, h) + (k ? boff1 : boff) + n * 2048); } } while (0)
; #define PG8_WAIT_V(n) asm volatile("s_waitcnt vmcnt(" #n ")" ::: "memory")
; #define PG8_WAIT_L(n) asm volatile("s_waitcnt lgkmcnt(" #n ")" ::: "memory")
; #define PG8_BAR __builtin_amdgcn_s_barrier()
; #define PG8_SCHED __builtin_amdgcn_sched_barrier(0)
; #define PG8_S1 PG8_STAGE(PG8_SA(1, 1), a1 + hstepA, voffA)
; #define PG8_S2 do { PG8_STAGE(PG8_SB(0, 0), b2, voffB); PG8_STAGE(PG8_SB(0, 1), b2 + hstepB, voffB); PG8_STAGE(PG8_SA(0, 0), a2, voffA); } while (0)
; template <class Epi, class SchedT, bool ALIGN_EPI, bool SP2, bool FP8 = false>
; __device__ __forceinline__ void gemm_phase(LAS unsigned char* lds, const Gemm g, const SchedT& S, const Epi& E, const int wid) {
;     ...
;         for (int t = 0; t < nt; t += 2) {
;             const bool last = (t == nt - 2);
;             const char* a1 = cA + (size_t)(t + 1) * kstep;
;             const char* a2 = last ? nA : cA + (size_t)(t + 2) * kstep; const char* b2 = last ? nB : cB + (size_t)(t + 2) * kstep;
;             const char* a3 = a2 + kstep; const char* b3 = b2 + kstep;
;             if constexpr (SP2) {
;     ...
;             PG8_LDB(B0, 0, 0); PG8_LDB(B1, 0, 1); PG8_SCHED; PG8_LDA(At, 0, 0); PG8_S1;
;             PG8_WAIT_V(8); PG8_WAIT_L(0); PG8_BAR; PG8_MMAP(0, 0, 0); PG8_BAR; PG8_SCHED;
;             PG8_LDA(At, 0, 1); PG8_S2;
;             PG8_WAIT_V(8); PG8_WAIT_L(0); PG8_BAR; PG8_MMAP(1, 0, 1); PG8_BAR; PG8_SCHED;
.LBB0_539:
	ds_read_b128 v[134:137], v215
	ds_read_b128 v[138:141], v215 offset:16
	ds_read_b128 v[142:145], v215 offset:2048
	ds_read_b128 v[146:149], v215 offset:2064
	ds_read_b128 v[150:153], v216
	ds_read_b128 v[154:157], v216 offset:16
	ds_read_b128 v[158:161], v216 offset:2048
	ds_read_b128 v[162:165], v216 offset:2064
	s_add_i32 s30, s10, 2
	s_add_u32 s16, s8, 0xfff70080
	s_addc_u32 s11, s9, -1
	s_cmp_eq_u32 s20, s10
	s_cselect_b32 s10, s52, s16
	s_cselect_b32 s11, s53, s11
	v_mov_b32_e32 v128, v210
	ds_read_b128 v[166:169], v217
	ds_read_b128 v[170:173], v217 offset:16
	ds_read_b128 v[174:177], v217 offset:2048
	ds_read_b128 v[178:181], v217 offset:2064
	ds_read_b128 v[182:185], v217 offset:4096
	ds_read_b128 v[186:189], v217 offset:4112
	ds_read_b128 v[190:193], v217 offset:6144
	ds_read_b128 v[194:197], v217 offset:6160
	s_cselect_b32 s67, s65, s24
	s_cselect_b32 s66, s64, s21
	s_add_i32 m0, s87, 0xc000
	s_nop 0
	global_load_lds_dwordx4 v128, s[8:9]
	v_mov_b32_e32 v128, v212
	s_add_i32 m0, s87, 0xe000
	s_nop 0
	global_load_lds_dwordx4 v128, s[8:9]
	s_waitcnt vmcnt(8)
	s_waitcnt lgkmcnt(0)
	s_setprio 1
	s_barrier
	v_mfma_scale_f32_16x16x128_f8f6f4 v[124:127], v[134:141], v[166:173], v[124:127], v218, v218 op_sel_hi:[0,0,0]
	v_mfma_scale_f32_16x16x128_f8f6f4 v[120:123], v[142:149], v[166:173], v[120:123], v218, v218 op_sel_hi:[0,0,0]
	v_mfma_scale_f32_16x16x128_f8f6f4 v[116:119], v[134:141], v[174:181], v[116:119], v218, v218 op_sel_hi:[0,0,0]
	v_mfma_scale_f32_16x16x128_f8f6f4 v[112:115], v[142:149], v[174:181], v[112:115], v218, v218 op_sel_hi:[0,0,0]
	v_mfma_scale_f32_16x16x128_f8f6f4 v[108:111], v[134:141], v[182:189], v[108:111], v218, v218 op_sel_hi:[0,0,0]
	v_mfma_scale_f32_16x16x128_f8f6f4 v[104:107], v[142:149], v[182:189], v[104:107], v218, v218 op_sel_hi:[0,0,0]
	v_mfma_scale_f32_16x16x128_f8f6f4 v[100:103], v[134:141], v[190:197], v[100:103], v218, v218 op_sel_hi:[0,0,0]
	v_mfma_scale_f32_16x16x128_f8f6f4 v[96:99], v[142:149], v[190:197], v[96:99], v218, v218 op_sel_hi:[0,0,0]
	v_mfma_scale_f32_16x16x128_f8f6f4 v[198:201], v[150:157], v[166:173], v[92:95], v218, v218 op_sel_hi:[0,0,0]
	v_mfma_scale_f32_16x16x128_f8f6f4 v[166:169], v[158:165], v[166:173], v[88:91], v218, v218 op_sel_hi:[0,0,0]
	v_mfma_scale_f32_16x16x128_f8f6f4 v[170:173], v[150:157], v[174:181], v[84:87], v218, v218 op_sel_hi:[0,0,0]
	v_mfma_scale_f32_16x16x128_f8f6f4 v[174:177], v[158:165], v[174:181], v[80:83], v218, v218 op_sel_hi:[0,0,0]
	v_mfma_scale_f32_16x16x128_f8f6f4 v[178:181], v[150:157], v[182:189], v[76:79], v218, v218 op_sel_hi:[0,0,0]
	v_mfma_scale_f32_16x16x128_f8f6f4 v[182:185], v[158:165], v[182:189], v[72:75], v218, v218 op_sel_hi:[0,0,0]
	v_mfma_scale_f32_16x16x128_f8f6f4 v[186:189], v[150:157], v[190:197], v[68:71], v218, v218 op_sel_hi:[0,0,0]
	v_mfma_scale_f32_16x16x128_f8f6f4 v[190:193], v[158:165], v[190:197], v[64:67], v218, v218 op_sel_hi:[0,0,0]
	s_barrier
	s_setprio 0
	v_mov_b32_e32 v128, v211
	s_add_i32 s16, s94, s86
	s_nop 2
	ds_read_b128 v[64:67], v217 offset:16384
	ds_read_b128 v[68:71], v217 offset:16400
	ds_read_b128 v[72:75], v217 offset:18432
	ds_read_b128 v[76:79], v217 offset:18448
	ds_read_b128 v[80:83], v217 offset:20480
	ds_read_b128 v[84:87], v217 offset:20496
	ds_read_b128 v[88:91], v217 offset:22528
	ds_read_b128 v[92:95], v217 offset:22544
	s_mov_b32 m0, s16
	s_nop 0
	global_load_lds_dwordx4 v128, s[66:67]
	v_mov_b32_e32 v128, v213
	s_add_i32 m0, s16, 0x2000
	s_add_u32 s60, s66, 0x88000
	global_load_lds_dwordx4 v128, s[66:67]
	s_addc_u32 s61, s67, 0
	v_mov_b32_e32 v128, v211
	s_add_i32 s16, s95, s86
	s_mov_b32 m0, s16
	s_nop 0
	global_load_lds_dwordx4 v128, s[60:61]
	v_mov_b32_e32 v128, v213
	s_add_i32 m0, s16, 0x2000
	s_nop 0
	global_load_lds_dwordx4 v128, s[60:61]
	v_mov_b32_e32 v128, v210
	s_mov_b32 m0, s87
	s_nop 0
	global_load_lds_dwordx4 v128, s[10:11]
	v_mov_b32_e32 v128, v212
	s_mov_b32 m0, s88
	s_nop 0
	global_load_lds_dwordx4 v128, s[10:11]
	s_waitcnt vmcnt(8)
	s_waitcnt lgkmcnt(0)
	s_setprio 1
	s_barrier
	v_mfma_scale_f32_16x16x128_f8f6f4 v[60:63], v[134:141], v[64:71], v[60:63], v218, v218 op_sel_hi:[0,0,0]
	v_mfma_scale_f32_16x16x128_f8f6f4 v[56:59], v[142:149], v[64:71], v[56:59], v218, v218 op_sel_hi:[0,0,0]
	v_mfma_scale_f32_16x16x128_f8f6f4 v[52:55], v[134:141], v[72:79], v[52:55], v218, v218 op_sel_hi:[0,0,0]
	v_mfma_scale_f32_16x16x128_f8f6f4 v[48:51], v[142:149], v[72:79], v[48:51], v218, v218 op_sel_hi:[0,0,0]
	v_mfma_scale_f32_16x16x128_f8f6f4 v[44:47], v[134:141], v[80:87], v[44:47], v218, v218 op_sel_hi:[0,0,0]
	v_mfma_scale_f32_16x16x128_f8f6f4 v[40:43], v[142:149], v[80:87], v[40:43], v218, v218 op_sel_hi:[0,0,0]
	v_mfma_scale_f32_16x16x128_f8f6f4 v[194:197], v[150:157], v[64:71], v[28:31], v218, v218 op_sel_hi:[0,0,0]
	v_mfma_scale_f32_16x16x128_f8f6f4 v[202:205], v[158:165], v[64:71], v[24:27], v218, v218 op_sel_hi:[0,0,0]
	v_mfma_scale_f32_16x16x128_f8f6f4 v[206:209], v[150:157], v[72:79], v[20:23], v218, v218 op_sel_hi:[0,0,0]
	v_mfma_scale_f32_16x16x128_f8f6f4 v[220:223], v[158:165], v[72:79], v[16:19], v218, v218 op_sel_hi:[0,0,0]
	v_mfma_scale_f32_16x16x128_f8f6f4 v[224:227], v[150:157], v[80:87], v[12:15], v218, v218 op_sel_hi:[0,0,0]
	v_mfma_scale_f32_16x16x128_f8f6f4 v[228:231], v[158:165], v[80:87], v[8:11], v218, v218 op_sel_hi:[0,0,0]
	v_mfma_scale_f32_16x16x128_f8f6f4 v[232:235], v[134:141], v[88:95], v[36:39], v218, v218 op_sel_hi:[0,0,0]
	v_mfma_scale_f32_16x16x128_f8f6f4 v[236:239], v[150:157], v[88:95], v[4:7], v218, v218 op_sel_hi:[0,0,0]
	v_mfma_scale_f32_16x16x128_f8f6f4 v[240:243], v[142:149], v[88:95], v[32:35], v218, v218 op_sel_hi:[0,0,0]
	v_mfma_scale_f32_16x16x128_f8f6f4 v[244:247], v[158:165], v[88:95], v[0:3], v218, v218 op_sel_hi:[0,0,0]
	s_barrier
; #define PG8_STAGE(bufoff, gbase, voff) do { _Pragma("unroll") for (int _i = 0; _i < 2; ++_i) { unsigned vo_ = (voff)[_i]; asm volatile("" : "+v"(vo_));     \
;         __builtin_amdgcn_global_load_lds((const unsigned*)((const char*)(gbase) + vo_), (LAS unsigned*)(lds + (bufoff) + ldsw + _i * 8192), 16, 0, 0); } } while (0)
; #define PG8_WAIT_V(n) asm volatile("s_waitcnt vmcnt(" #n ")" ::: "memory")
; #define PG8_WAIT_L(n) asm volatile("s_waitcnt lgkmcnt(" #n ")" ::: "memory")
; template <class Epi, class SchedT, bool ALIGN_EPI, bool SP2, bool FP8 = false>
; __device__ __forceinline__ void gemm_phase(LAS unsigned char* lds, const Gemm g, const SchedT& S, const Epi& E, const int wid) {
;     ...
;             PG8_LDB(B0, 1, 0); PG8_LDB(B1, 1, 1); PG8_SCHED; PG8_LDA(At, 1, 0); PG8_S3;
;             PG8_WAIT_V(8); PG8_WAIT_L(0); PG8_BAR; PG8_MMAP(0, 1, 0); PG8_BAR; PG8_SCHED;
;             PG8_LDA(At, 1, 1); PG8_S4;
;             PG8_WAIT_V(8); PG8_WAIT_L(0); PG8_BAR; PG8_MMAP(1, 1, 1); PG8_BAR; PG8_SCHED;
;             } else {
;             PG8_LDB(B0, 0, 0); PG8_SCHED; PG8_LDA(At, 0, 0); PG8_STAGE(PG8_SA(1, 1), a1 + hstepA, voffA);
;             PG8_WAIT_L(8); PG8_BAR; PG8_WAIT_L(0); PG8_MMA(0, 0, At, B0); PG8_BAR; PG8_SCHED;
;             PG8_LDB(B1, 0, 1); PG8_STAGE(PG8_SB(0, 0), b2, voffB);
;             PG8_BAR; PG8_WAIT_L(0); PG8_MMA(0, 1, At, B1); PG8_BAR;
;             PG8_LDA(At, 0, 1); PG8_STAGE(PG8_SA(0, 0), a2, voffA);
;             PG8_BAR; PG8_WAIT_L(0); PG8_MMA(1, 0, At, B0); PG8_BAR; PG8_SCHED;
;             PG8_STAGE(PG8_SB(0, 1), b2 + hstepB, voffB);
;             PG8_WAIT_V(6); PG8_BAR; PG8_MMA(1, 1, At, B1); PG8_BAR;
;             PG8_LDB(B0, 1, 0); PG8_SCHED; PG8_LDA(At, 1, 0); PG8_STAGE(PG8_SA(0, 1), a2 + hstepA, voffA);
;             PG8_WAIT_L(8); PG8_BAR; PG8_WAIT_L(0); PG8_MMA(0, 0, At, B0); PG8_BAR; PG8_SCHED;
;             PG8_LDB(B1, 1, 1); PG8_STAGE(PG8_SB(1, 0), b3, voffB);
;             PG8_BAR; PG8_WAIT_L(0); PG8_MMA(0, 1, At, B1); PG8_BAR;
;             PG8_LDA(At, 1, 1); PG8_STAGE(PG8_SA(1, 0), a3, voffA);
;             PG8_BAR; PG8_WAIT_L(0); PG8_MMA(1, 0, At, B0); PG8_BAR; PG8_SCHED;
;             PG8_STAGE(PG8_SB(1, 1), b3 + hstepB, voffB);
;             PG8_WAIT_V(6); PG8_BAR; PG8_MMA(1, 1, At, B1); PG8_BAR;
;             }
;         }
;         if constexpr (ALIGN_EPI) { if (wr == 0) PG8_BAR; }
	s_setprio 0
	s_add_i32 s16, 0, 0x18000
	v_add_u32_e32 v8, s16, v214
	s_add_i32 s17, 0, 0x1c000
	s_nop 1
	ds_read_b128 v[0:3], v8
	ds_read_b128 v[4:7], v8 offset:16
	ds_read_b128 v[134:137], v8 offset:2048
	ds_read_b128 v[138:141], v8 offset:2064
	v_add_u32_e32 v8, s17, v214
	ds_read_b128 v[142:145], v8
	ds_read_b128 v[146:149], v8 offset:16
	ds_read_b128 v[150:153], v8 offset:2048
	ds_read_b128 v[154:157], v8 offset:2064
	s_add_u32 s60, s10, 0x90000
	v_mov_b32_e32 v64, v210
	s_mov_b32 m0, s89
	ds_read_b128 v[8:11], v217 offset:32768
	ds_read_b128 v[12:15], v217 offset:32784
	ds_read_b128 v[16:19], v217 offset:34816
	ds_read_b128 v[20:23], v217 offset:34832
	ds_read_b128 v[24:27], v217 offset:36864
	ds_read_b128 v[28:31], v217 offset:36880
	ds_read_b128 v[32:35], v217 offset:38912
	ds_read_b128 v[36:39], v217 offset:38928
	s_addc_u32 s61, s11, 0
	s_nop 0
	global_load_lds_dwordx4 v64, s[60:61]
	v_mov_b32_e32 v64, v212
	s_mov_b32 m0, s90
	s_nop 0
	global_load_lds_dwordx4 v64, s[60:61]
	s_waitcnt vmcnt(8)
	s_waitcnt lgkmcnt(0)
	s_setprio 1
	s_barrier
	v_mfma_scale_f32_16x16x128_f8f6f4 v[124:127], v[0:7], v[8:15], v[124:127], v218, v218 op_sel_hi:[0,0,0]
	v_mfma_scale_f32_16x16x128_f8f6f4 v[92:95], v[142:149], v[8:15], v[198:201], v218, v218 op_sel_hi:[0,0,0]
	v_mfma_scale_f32_16x16x128_f8f6f4 v[120:123], v[134:141], v[8:15], v[120:123], v218, v218 op_sel_hi:[0,0,0]
	v_mfma_scale_f32_16x16x128_f8f6f4 v[88:91], v[150:157], v[8:15], v[166:169], v218, v218 op_sel_hi:[0,0,0]
	v_mfma_scale_f32_16x16x128_f8f6f4 v[116:119], v[0:7], v[16:23], v[116:119], v218, v218 op_sel_hi:[0,0,0]
	v_mfma_scale_f32_16x16x128_f8f6f4 v[84:87], v[142:149], v[16:23], v[170:173], v218, v218 op_sel_hi:[0,0,0]
	v_mfma_scale_f32_16x16x128_f8f6f4 v[112:115], v[134:141], v[16:23], v[112:115], v218, v218 op_sel_hi:[0,0,0]
	v_mfma_scale_f32_16x16x128_f8f6f4 v[80:83], v[150:157], v[16:23], v[174:177], v218, v218 op_sel_hi:[0,0,0]
	v_mfma_scale_f32_16x16x128_f8f6f4 v[108:111], v[0:7], v[24:31], v[108:111], v218, v218 op_sel_hi:[0,0,0]
	v_mfma_scale_f32_16x16x128_f8f6f4 v[76:79], v[142:149], v[24:31], v[178:181], v218, v218 op_sel_hi:[0,0,0]
	v_mfma_scale_f32_16x16x128_f8f6f4 v[104:107], v[134:141], v[24:31], v[104:107], v218, v218 op_sel_hi:[0,0,0]
	v_mfma_scale_f32_16x16x128_f8f6f4 v[72:75], v[150:157], v[24:31], v[182:185], v218, v218 op_sel_hi:[0,0,0]
	v_mfma_scale_f32_16x16x128_f8f6f4 v[100:103], v[0:7], v[32:39], v[100:103], v218, v218 op_sel_hi:[0,0,0]
	v_mfma_scale_f32_16x16x128_f8f6f4 v[68:71], v[142:149], v[32:39], v[186:189], v218, v218 op_sel_hi:[0,0,0]
	v_mfma_scale_f32_16x16x128_f8f6f4 v[96:99], v[134:141], v[32:39], v[96:99], v218, v218 op_sel_hi:[0,0,0]
	v_mfma_scale_f32_16x16x128_f8f6f4 v[64:67], v[150:157], v[32:39], v[190:193], v218, v218 op_sel_hi:[0,0,0]
	s_barrier
	s_setprio 0
	v_mov_b32_e32 v128, v211
	ds_read_b128 v[8:11], v217 offset:49152
	ds_read_b128 v[12:15], v217 offset:49168
	ds_read_b128 v[32:35], v217 offset:51200
	ds_read_b128 v[36:39], v217 offset:51216
	ds_read_b128 v[158:161], v217 offset:53248
	ds_read_b128 v[162:165], v217 offset:53264
	ds_read_b128 v[166:169], v217 offset:55296
	ds_read_b128 v[170:173], v217 offset:55312
	s_add_i32 s16, s16, s86
	v_lshl_add_u64 v[16:17], s[66:67], 0, v[128:129]
	v_lshl_add_u64 v[16:17], v[16:17], 0, s[44:45]
	s_mov_b32 m0, s16
	v_mov_b32_e32 v128, v213
	global_load_lds_dwordx4 v[16:17], off
	s_add_i32 m0, s16, 0x2000
	v_lshl_add_u64 v[16:17], s[66:67], 0, v[128:129]
	v_lshl_add_u64 v[16:17], v[16:17], 0, s[44:45]
	s_add_u32 s60, s66, 0x88080
	global_load_lds_dwordx4 v[16:17], off
	s_addc_u32 s61, s67, 0
	v_mov_b32_e32 v16, v211
	s_add_i32 s16, s17, s86
	s_mov_b32 m0, s16
	v_mov_b32_e32 v128, v210
	global_load_lds_dwordx4 v16, s[60:61]
	v_mov_b32_e32 v16, v213
	s_add_i32 m0, s16, 0x2000
	s_nop 0
	global_load_lds_dwordx4 v16, s[60:61]
	s_mov_b32 m0, s92
	v_lshl_add_u64 v[16:17], s[10:11], 0, v[128:129]
	v_lshl_add_u64 v[16:17], v[16:17], 0, s[44:45]
	v_mov_b32_e32 v128, v212
	global_load_lds_dwordx4 v[16:17], off
	s_mov_b32 m0, s93
	v_lshl_add_u64 v[16:17], s[10:11], 0, v[128:129]
	v_lshl_add_u64 v[16:17], v[16:17], 0, s[44:45]
	global_load_lds_dwordx4 v[16:17], off
	s_waitcnt vmcnt(8)
	s_waitcnt lgkmcnt(0)
	s_setprio 1
	s_barrier
	v_mfma_scale_f32_16x16x128_f8f6f4 v[60:63], v[0:7], v[8:15], v[60:63], v218, v218 op_sel_hi:[0,0,0]
	v_mfma_scale_f32_16x16x128_f8f6f4 v[28:31], v[142:149], v[8:15], v[194:197], v218, v218 op_sel_hi:[0,0,0]
	v_mfma_scale_f32_16x16x128_f8f6f4 v[56:59], v[134:141], v[8:15], v[56:59], v218, v218 op_sel_hi:[0,0,0]
	v_mfma_scale_f32_16x16x128_f8f6f4 v[24:27], v[150:157], v[8:15], v[202:205], v218, v218 op_sel_hi:[0,0,0]
	v_mfma_scale_f32_16x16x128_f8f6f4 v[52:55], v[0:7], v[32:39], v[52:55], v218, v218 op_sel_hi:[0,0,0]
	v_mfma_scale_f32_16x16x128_f8f6f4 v[20:23], v[142:149], v[32:39], v[206:209], v218, v218 op_sel_hi:[0,0,0]
	v_mfma_scale_f32_16x16x128_f8f6f4 v[48:51], v[134:141], v[32:39], v[48:51], v218, v218 op_sel_hi:[0,0,0]
	v_mfma_scale_f32_16x16x128_f8f6f4 v[16:19], v[150:157], v[32:39], v[220:223], v218, v218 op_sel_hi:[0,0,0]
	v_mfma_scale_f32_16x16x128_f8f6f4 v[44:47], v[0:7], v[158:165], v[44:47], v218, v218 op_sel_hi:[0,0,0]
	v_mfma_scale_f32_16x16x128_f8f6f4 v[12:15], v[142:149], v[158:165], v[224:227], v218, v218 op_sel_hi:[0,0,0]
	v_mfma_scale_f32_16x16x128_f8f6f4 v[40:43], v[134:141], v[158:165], v[40:43], v218, v218 op_sel_hi:[0,0,0]
	v_mfma_scale_f32_16x16x128_f8f6f4 v[8:11], v[150:157], v[158:165], v[228:231], v218, v218 op_sel_hi:[0,0,0]
	v_mfma_scale_f32_16x16x128_f8f6f4 v[36:39], v[0:7], v[166:173], v[232:235], v218, v218 op_sel_hi:[0,0,0]
	v_mfma_scale_f32_16x16x128_f8f6f4 v[4:7], v[142:149], v[166:173], v[236:239], v218, v218 op_sel_hi:[0,0,0]
	v_mfma_scale_f32_16x16x128_f8f6f4 v[32:35], v[134:141], v[166:173], v[240:243], v218, v218 op_sel_hi:[0,0,0]
	v_mfma_scale_f32_16x16x128_f8f6f4 v[0:3], v[150:157], v[166:173], v[244:247], v218, v218 op_sel_hi:[0,0,0]
	s_barrier
	s_setprio 0
	s_add_u32 s8, s8, 0x100
	s_addc_u32 s9, s9, 0
	s_add_u32 s21, s21, 0x100
	s_addc_u32 s24, s24, 0
	s_cmp_ge_i32 s30, s71
	s_mov_b32 s10, s30
	s_cbranch_scc0 .LBB0_539
	s_and_b64 vcc, exec, s[96:97]
	s_cbranch_vccz .LBB0_542

; #define PG8_LDA(dst, b, h) do { if constexpr (FP8) { _Pragma("unroll") for (int m = 0; m < 4; ++m) dst##8[m] = PG8_LD8(PG8_SA(b, h), aoff, aoff1, m); } \
;         else { _Pragma("unroll") for (int m = 0; m < 4; ++m) _Pragma("unroll") for (int k = 0; k < 2; ++k) dst[m][k] = *(const LAS bf16x8*)(lds + PG8_SA(b, h) + (k ? aoff1 : aoff) + m * 2048); } } while (0)
; #define PG8_LDB(dst, b, h) do { if constexpr (FP8) { dst##8[0] = PG8_LD8(PG8_SB(b, h), boff, boff1, 0); dst##8[1] = PG8_LD8(PG8_SB(b, h), boff, boff1, 1); } \
;         else { _Pragma("unroll") for (int n = 0; n < 2; ++n) _Pragma("unroll") for (int k = 0; k < 2; ++k) dst[n][k] = *(const LAS bf16x8*)(lds + PG8_SB(b, h) + (k ? boff1 : boff) + n * 2048); } } while (0)
; #define PG8_WAIT_V(n) asm volatile("s_waitcnt vmcnt(" #n ")" ::: "memory")
; #define PG8_WAIT_L(n) asm volatile("s_waitcnt lgkmcnt(" #n ")" ::: "memory")
; #define PG8_BAR __builtin_amdgcn_s_barrier()
; #define PG8_SCHED __builtin_amdgcn_sched_barrier(0)
; #define PG8_S1 PG8_STAGE(PG8_SA(1, 1), a1 + hstepA, voffA)
; #define PG8_S2 do { PG8_STAGE(PG8_SB(0, 0), b2, voffB); PG8_STAGE(PG8_SB(0, 1), b2 + hstepB, voffB); PG8_STAGE(PG8_SA(0, 0), a2, voffA); } while (0)
; template <class Epi, class SchedT, bool ALIGN_EPI, bool SP2, bool FP8 = false>
; __device__ __forceinline__ void gemm_phase(LAS unsigned char* lds, const Gemm g, const SchedT& S, const Epi& E, const int wid) {
;     ...
;         for (int t = 0; t < nt; t += 2) {
;             const bool last = (t == nt - 2);
;             const char* a1 = cA + (size_t)(t + 1) * kstep;
;             const char* a2 = last ? nA : cA + (size_t)(t + 2) * kstep; const char* b2 = last ? nB : cB + (size_t)(t + 2) * kstep;
;             const char* a3 = a2 + kstep; const char* b3 = b2 + kstep;
;             if constexpr (SP2) {
;     ...
;             PG8_LDB(B0, 0, 0); PG8_LDB(B1, 0, 1); PG8_SCHED; PG8_LDA(At, 0, 0); PG8_S1;
;             PG8_WAIT_V(8); PG8_WAIT_L(0); PG8_BAR; PG8_MMAP(0, 0, 0); PG8_BAR; PG8_SCHED;
;             PG8_LDA(At, 0, 1); PG8_S2;
;             PG8_WAIT_V(8); PG8_WAIT_L(0); PG8_BAR; PG8_MMAP(1, 0, 1); PG8_BAR; PG8_SCHED;
.LBB0_779:
	ds_read_b128 v[134:137], v149
	ds_read_b128 v[138:141], v149 offset:16
	ds_read_b128 v[154:157], v149 offset:2048
	ds_read_b128 v[158:161], v149 offset:2064
	ds_read_b128 v[162:165], v150
	ds_read_b128 v[166:169], v150 offset:16
	ds_read_b128 v[170:173], v150 offset:2048
	ds_read_b128 v[174:177], v150 offset:2064
	s_add_i32 s45, s47, 2
	s_add_u32 s16, s52, 0xfffe0080
	s_addc_u32 s17, s53, -1
	s_cmp_eq_u32 s24, s47
	s_cselect_b32 s65, s9, s17
	s_cselect_b32 s64, s21, s16
	v_mov_b32_e32 v128, v146
	ds_read_b128 v[178:181], v151
	ds_read_b128 v[182:185], v151 offset:16
	ds_read_b128 v[186:189], v151 offset:2048
	ds_read_b128 v[190:193], v151 offset:2064
	ds_read_b128 v[194:197], v151 offset:4096
	ds_read_b128 v[198:201], v151 offset:4112
	ds_read_b128 v[202:205], v151 offset:6144
	ds_read_b128 v[206:209], v151 offset:6160
	s_cselect_b32 s67, s22, s31
	s_cselect_b32 s66, s23, s30
	s_add_i32 m0, s87, 0xc000
	s_nop 0
	global_load_lds_dwordx4 v128, s[52:53]
	v_mov_b32_e32 v128, v147
	s_add_i32 m0, s87, 0xe000
	s_nop 0
	global_load_lds_dwordx4 v128, s[52:53]
	s_waitcnt vmcnt(8)
	s_waitcnt lgkmcnt(0)
	s_setprio 1
	s_barrier
	v_mfma_scale_f32_16x16x128_f8f6f4 v[124:127], v[134:141], v[178:185], v[124:127], v152, v152 op_sel_hi:[0,0,0]
	v_mfma_scale_f32_16x16x128_f8f6f4 v[108:111], v[162:169], v[178:185], v[108:111], v152, v152 op_sel_hi:[0,0,0]
	v_mfma_scale_f32_16x16x128_f8f6f4 v[120:123], v[154:161], v[178:185], v[120:123], v152, v152 op_sel_hi:[0,0,0]
	v_mfma_scale_f32_16x16x128_f8f6f4 v[100:103], v[170:177], v[178:185], v[100:103], v152, v152 op_sel_hi:[0,0,0]
	v_mfma_scale_f32_16x16x128_f8f6f4 v[116:119], v[134:141], v[186:193], v[116:119], v152, v152 op_sel_hi:[0,0,0]
	v_mfma_scale_f32_16x16x128_f8f6f4 v[112:115], v[154:161], v[186:193], v[112:115], v152, v152 op_sel_hi:[0,0,0]
	v_mfma_scale_f32_16x16x128_f8f6f4 v[104:107], v[134:141], v[194:201], v[104:107], v152, v152 op_sel_hi:[0,0,0]
	v_mfma_scale_f32_16x16x128_f8f6f4 v[60:63], v[170:177], v[202:209], v[60:63], v152, v152 op_sel_hi:[0,0,0]
	v_mfma_scale_f32_16x16x128_f8f6f4 v[142:145], v[162:169], v[186:193], v[92:95], v152, v152 op_sel_hi:[0,0,0]
	v_mfma_scale_f32_16x16x128_f8f6f4 v[178:181], v[170:177], v[186:193], v[84:87], v152, v152 op_sel_hi:[0,0,0]
	v_mfma_scale_f32_16x16x128_f8f6f4 v[182:185], v[162:169], v[194:201], v[76:79], v152, v152 op_sel_hi:[0,0,0]
	v_mfma_scale_f32_16x16x128_f8f6f4 v[186:189], v[154:161], v[194:201], v[96:99], v152, v152 op_sel_hi:[0,0,0]
	v_mfma_scale_f32_16x16x128_f8f6f4 v[190:193], v[170:177], v[194:201], v[72:75], v152, v152 op_sel_hi:[0,0,0]
	v_mfma_scale_f32_16x16x128_f8f6f4 v[194:197], v[134:141], v[202:209], v[88:91], v152, v152 op_sel_hi:[0,0,0]
	v_mfma_scale_f32_16x16x128_f8f6f4 v[198:201], v[162:169], v[202:209], v[68:71], v152, v152 op_sel_hi:[0,0,0]
	v_mfma_scale_f32_16x16x128_f8f6f4 v[210:213], v[154:161], v[202:209], v[80:83], v152, v152 op_sel_hi:[0,0,0]
	s_barrier
	s_setprio 0
	v_mov_b32_e32 v128, v146
	s_add_i32 s16, s94, s86
	s_nop 1
	ds_read_b128 v[68:71], v151 offset:16384
	ds_read_b128 v[72:75], v151 offset:16400
	ds_read_b128 v[76:79], v151 offset:18432
	ds_read_b128 v[80:83], v151 offset:18448
	ds_read_b128 v[84:87], v151 offset:20480
	ds_read_b128 v[88:91], v151 offset:20496
	ds_read_b128 v[92:95], v151 offset:22528
	ds_read_b128 v[96:99], v151 offset:22544
	s_mov_b32 m0, s16
	s_nop 0
	global_load_lds_dwordx4 v128, s[66:67]
	v_mov_b32_e32 v128, v147
	s_add_i32 m0, s16, 0x2000
	s_add_u32 s60, s66, 0x20000
	global_load_lds_dwordx4 v128, s[66:67]
	s_addc_u32 s61, s67, 0
	v_mov_b32_e32 v128, v146
	s_add_i32 s16, s95, s86
	s_mov_b32 m0, s16
	s_nop 0
	global_load_lds_dwordx4 v128, s[60:61]
	v_mov_b32_e32 v128, v147
	s_add_i32 m0, s16, 0x2000
	s_nop 0
	global_load_lds_dwordx4 v128, s[60:61]
	v_mov_b32_e32 v128, v146
	s_mov_b32 m0, s87
	s_nop 0
	global_load_lds_dwordx4 v128, s[64:65]
	v_mov_b32_e32 v128, v147
	s_mov_b32 m0, s88
	s_nop 0
	global_load_lds_dwordx4 v128, s[64:65]
	s_waitcnt vmcnt(8)
	s_waitcnt lgkmcnt(0)
	s_setprio 1
	s_barrier
	v_mfma_scale_f32_16x16x128_f8f6f4 v[64:67], v[134:141], v[68:75], v[64:67], v152, v152 op_sel_hi:[0,0,0]
	v_mfma_scale_f32_16x16x128_f8f6f4 v[44:47], v[162:169], v[68:75], v[44:47], v152, v152 op_sel_hi:[0,0,0]
	v_mfma_scale_f32_16x16x128_f8f6f4 v[56:59], v[154:161], v[68:75], v[56:59], v152, v152 op_sel_hi:[0,0,0]
	v_mfma_scale_f32_16x16x128_f8f6f4 v[52:55], v[134:141], v[76:83], v[52:55], v152, v152 op_sel_hi:[0,0,0]
	v_mfma_scale_f32_16x16x128_f8f6f4 v[48:51], v[154:161], v[76:83], v[48:51], v152, v152 op_sel_hi:[0,0,0]
	v_mfma_scale_f32_16x16x128_f8f6f4 v[40:43], v[134:141], v[84:91], v[40:43], v152, v152 op_sel_hi:[0,0,0]
	v_mfma_scale_f32_16x16x128_f8f6f4 v[202:205], v[170:177], v[68:75], v[36:39], v152, v152 op_sel_hi:[0,0,0]
	v_mfma_scale_f32_16x16x128_f8f6f4 v[206:209], v[162:169], v[76:83], v[28:31], v152, v152 op_sel_hi:[0,0,0]
	v_mfma_scale_f32_16x16x128_f8f6f4 v[214:217], v[170:177], v[76:83], v[20:23], v152, v152 op_sel_hi:[0,0,0]
	v_mfma_scale_f32_16x16x128_f8f6f4 v[218:221], v[162:169], v[84:91], v[12:15], v152, v152 op_sel_hi:[0,0,0]
	v_mfma_scale_f32_16x16x128_f8f6f4 v[222:225], v[154:161], v[84:91], v[32:35], v152, v152 op_sel_hi:[0,0,0]
	v_mfma_scale_f32_16x16x128_f8f6f4 v[226:229], v[170:177], v[84:91], v[8:11], v152, v152 op_sel_hi:[0,0,0]
	v_mfma_scale_f32_16x16x128_f8f6f4 v[230:233], v[134:141], v[92:99], v[24:27], v152, v152 op_sel_hi:[0,0,0]
	v_mfma_scale_f32_16x16x128_f8f6f4 v[234:237], v[162:169], v[92:99], v[4:7], v152, v152 op_sel_hi:[0,0,0]
	v_mfma_scale_f32_16x16x128_f8f6f4 v[238:241], v[154:161], v[92:99], v[16:19], v152, v152 op_sel_hi:[0,0,0]
	v_mfma_scale_f32_16x16x128_f8f6f4 v[242:245], v[170:177], v[92:99], v[0:3], v152, v152 op_sel_hi:[0,0,0]
	s_barrier
; #define PG8_LDA(dst, b, h) do { if constexpr (FP8) { _Pragma("unroll") for (int m = 0; m < 4; ++m) dst##8[m] = PG8_LD8(PG8_SA(b, h), aoff, aoff1, m); } \
;         else { _Pragma("unroll") for (int m = 0; m < 4; ++m) _Pragma("unroll") for (int k = 0; k < 2; ++k) dst[m][k] = *(const LAS bf16x8*)(lds + PG8_SA(b, h) + (k ? aoff1 : aoff) + m * 2048); } } while (0)
; #define PG8_LDB(dst, b, h) do { if constexpr (FP8) { dst##8[0] = PG8_LD8(PG8_SB(b, h), boff, boff1, 0); dst##8[1] = PG8_LD8(PG8_SB(b, h), boff, boff1, 1); } \
;         else { _Pragma("unroll") for (int n = 0; n < 2; ++n) _Pragma("unroll") for (int k = 0; k < 2; ++k) dst[n][k] = *(const LAS bf16x8*)(lds + PG8_SB(b, h) + (k ? boff1 : boff) + n * 2048); } } while (0)
; #define PG8_WAIT_V(n) asm volatile("s_waitcnt vmcnt(" #n ")" ::: "memory")
; #define PG8_WAIT_L(n) asm volatile("s_waitcnt lgkmcnt(" #n ")" ::: "memory")
; #define PG8_BAR __builtin_amdgcn_s_barrier()
; #define PG8_SCHED __builtin_amdgcn_sched_barrier(0)
; #define PG8_S2 do { PG8_STAGE(PG8_SB(0, 0), b2, voffB); PG8_STAGE(PG8_SB(0, 1), b2 + hstepB, voffB); PG8_STAGE(PG8_SA(0, 0), a2, voffA); } while (0)
; #define PG8_S3 PG8_STAGE(PG8_SA(0, 1), a2 + hstepA, voffA)
; template <class Epi, class SchedT, bool ALIGN_EPI, bool SP2, bool FP8 = false>
; __device__ __forceinline__ void gemm_phase(LAS unsigned char* lds, const Gemm g, const SchedT& S, const Epi& E, const int wid) {
;     ...
;             PG8_WAIT_V(8); PG8_WAIT_L(0); PG8_BAR; PG8_MMAP(0, 0, 0); PG8_BAR; PG8_SCHED;
;             PG8_LDA(At, 0, 1); PG8_S2;
;             PG8_WAIT_V(8); PG8_WAIT_L(0); PG8_BAR; PG8_MMAP(1, 0, 1); PG8_BAR; PG8_SCHED;
;             PG8_LDB(B0, 1, 0); PG8_LDB(B1, 1, 1); PG8_SCHED; PG8_LDA(At, 1, 0); PG8_S3;
;             PG8_WAIT_V(8); PG8_WAIT_L(0); PG8_BAR; PG8_MMAP(0, 1, 0); PG8_BAR; PG8_SCHED;
	s_setprio 0
	s_add_i32 s16, 0, 0x18000
	v_add_u32_e32 v8, s16, v148
	s_add_i32 s17, 0, 0x1c000
	s_nop 1
	ds_read_b128 v[0:3], v8
	ds_read_b128 v[4:7], v8 offset:16
	ds_read_b128 v[134:137], v8 offset:2048
	ds_read_b128 v[138:141], v8 offset:2064
	v_add_u32_e32 v8, s17, v148
	ds_read_b128 v[154:157], v8
	ds_read_b128 v[158:161], v8 offset:16
	ds_read_b128 v[162:165], v8 offset:2048
	ds_read_b128 v[166:169], v8 offset:2064
	s_add_u32 s60, s64, 0x20000
	v_mov_b32_e32 v68, v146
	s_mov_b32 m0, s89
	ds_read_b128 v[8:11], v151 offset:32768
	ds_read_b128 v[12:15], v151 offset:32784
	ds_read_b128 v[16:19], v151 offset:34816
	ds_read_b128 v[20:23], v151 offset:34832
	ds_read_b128 v[24:27], v151 offset:36864
	ds_read_b128 v[28:31], v151 offset:36880
	ds_read_b128 v[32:35], v151 offset:38912
	ds_read_b128 v[36:39], v151 offset:38928
	s_addc_u32 s61, s65, 0
	s_nop 0
	global_load_lds_dwordx4 v68, s[60:61]
	v_mov_b32_e32 v68, v147
	s_mov_b32 m0, s90
	s_nop 0
	global_load_lds_dwordx4 v68, s[60:61]
	s_waitcnt vmcnt(8)
	s_waitcnt lgkmcnt(0)
	s_setprio 1
	s_barrier
	v_mfma_scale_f32_16x16x128_f8f6f4 v[124:127], v[0:7], v[8:15], v[124:127], v152, v152 op_sel_hi:[0,0,0]
	v_mfma_scale_f32_16x16x128_f8f6f4 v[108:111], v[154:161], v[8:15], v[108:111], v152, v152 op_sel_hi:[0,0,0]
	v_mfma_scale_f32_16x16x128_f8f6f4 v[120:123], v[134:141], v[8:15], v[120:123], v152, v152 op_sel_hi:[0,0,0]
	v_mfma_scale_f32_16x16x128_f8f6f4 v[100:103], v[162:169], v[8:15], v[100:103], v152, v152 op_sel_hi:[0,0,0]
	v_mfma_scale_f32_16x16x128_f8f6f4 v[116:119], v[0:7], v[16:23], v[116:119], v152, v152 op_sel_hi:[0,0,0]
	v_mfma_scale_f32_16x16x128_f8f6f4 v[92:95], v[154:161], v[16:23], v[142:145], v152, v152 op_sel_hi:[0,0,0]
	v_mfma_scale_f32_16x16x128_f8f6f4 v[112:115], v[134:141], v[16:23], v[112:115], v152, v152 op_sel_hi:[0,0,0]
	v_mfma_scale_f32_16x16x128_f8f6f4 v[84:87], v[162:169], v[16:23], v[178:181], v152, v152 op_sel_hi:[0,0,0]
	v_mfma_scale_f32_16x16x128_f8f6f4 v[104:107], v[0:7], v[24:31], v[104:107], v152, v152 op_sel_hi:[0,0,0]
	v_mfma_scale_f32_16x16x128_f8f6f4 v[76:79], v[154:161], v[24:31], v[182:185], v152, v152 op_sel_hi:[0,0,0]
	v_mfma_scale_f32_16x16x128_f8f6f4 v[96:99], v[134:141], v[24:31], v[186:189], v152, v152 op_sel_hi:[0,0,0]
	v_mfma_scale_f32_16x16x128_f8f6f4 v[72:75], v[162:169], v[24:31], v[190:193], v152, v152 op_sel_hi:[0,0,0]
	v_mfma_scale_f32_16x16x128_f8f6f4 v[88:91], v[0:7], v[32:39], v[194:197], v152, v152 op_sel_hi:[0,0,0]
	v_mfma_scale_f32_16x16x128_f8f6f4 v[68:71], v[154:161], v[32:39], v[198:201], v152, v152 op_sel_hi:[0,0,0]
	v_mfma_scale_f32_16x16x128_f8f6f4 v[80:83], v[134:141], v[32:39], v[210:213], v152, v152 op_sel_hi:[0,0,0]
	v_mfma_scale_f32_16x16x128_f8f6f4 v[60:63], v[162:169], v[32:39], v[60:63], v152, v152 op_sel_hi:[0,0,0]
	s_barrier
	s_setprio 0
	v_mov_b32_e32 v128, v146
	ds_read_b128 v[8:11], v151 offset:49152
	ds_read_b128 v[12:15], v151 offset:49168
	ds_read_b128 v[16:19], v151 offset:51200
	ds_read_b128 v[20:23], v151 offset:51216
	ds_read_b128 v[170:173], v151 offset:53248
	ds_read_b128 v[174:177], v151 offset:53264
	ds_read_b128 v[178:181], v151 offset:55296
	ds_read_b128 v[182:185], v151 offset:55312
	s_add_i32 s16, s16, s86
	v_lshl_add_u64 v[24:25], s[66:67], 0, v[128:129]
	v_lshl_add_u64 v[24:25], v[24:25], 0, s[26:27]
	s_mov_b32 m0, s16
	v_mov_b32_e32 v128, v147
	global_load_lds_dwordx4 v[24:25], off
	s_add_i32 m0, s16, 0x2000
	v_lshl_add_u64 v[24:25], s[66:67], 0, v[128:129]
	v_lshl_add_u64 v[24:25], v[24:25], 0, s[26:27]
	s_add_u32 s60, s66, 0x20080
	global_load_lds_dwordx4 v[24:25], off
	s_addc_u32 s61, s67, 0
	v_mov_b32_e32 v24, v146
	s_add_i32 s16, s17, s86
	s_mov_b32 m0, s16
	v_mov_b32_e32 v128, v146
	global_load_lds_dwordx4 v24, s[60:61]
	v_mov_b32_e32 v24, v147
	s_add_i32 m0, s16, 0x2000
	s_nop 0
	global_load_lds_dwordx4 v24, s[60:61]
	s_mov_b32 m0, s92
	v_lshl_add_u64 v[24:25], s[64:65], 0, v[128:129]
	v_lshl_add_u64 v[24:25], v[24:25], 0, s[26:27]
	v_mov_b32_e32 v128, v147
	global_load_lds_dwordx4 v[24:25], off
	s_mov_b32 m0, s93
	v_lshl_add_u64 v[24:25], s[64:65], 0, v[128:129]
	v_lshl_add_u64 v[24:25], v[24:25], 0, s[26:27]
	global_load_lds_dwordx4 v[24:25], off
	s_waitcnt vmcnt(8)
	s_waitcnt lgkmcnt(0)
	s_setprio 1
	s_barrier
; #define PG8_LDA(dst, b, h) do { if constexpr (FP8) { _Pragma("unroll") for (int m = 0; m < 4; ++m) dst##8[m] = PG8_LD8(PG8_SA(b, h), aoff, aoff1, m); } \
;         else { _Pragma("unroll") for (int m = 0; m < 4; ++m) _Pragma("unroll") for (int k = 0; k < 2; ++k) dst[m][k] = *(const LAS bf16x8*)(lds + PG8_SA(b, h) + (k ? aoff1 : aoff) + m * 2048); } } while (0)
; #define PG8_WAIT_V(n) asm volatile("s_waitcnt vmcnt(" #n ")" ::: "memory")
; #define PG8_WAIT_L(n) asm volatile("s_waitcnt lgkmcnt(" #n ")" ::: "memory")
; #define PG8_BAR __builtin_amdgcn_s_barrier()
; #define PG8_SCHED __builtin_amdgcn_sched_barrier(0)
; #define PG8_S4 do { PG8_STAGE(PG8_SB(1, 0), b3, voffB); PG8_STAGE(PG8_SB(1, 1), b3 + hstepB, voffB); PG8_STAGE(PG8_SA(1, 0), a3, voffA); } while (0)
;     __device__ __forceinline__ void operator()(const f32x4 (&acc)[2][2][4][2], const Unit& u, int wr, int wc, int fr, int fq) const {
;     ...
;                     for (int n = 0; n < 2; ++n) { const int co = bj * HALF + n * 16; const f32x4 v = *(const f32x4*)(xr + co) + acc[ai][bj][m][n] * sc;
; template <class Epi, class SchedT, bool ALIGN_EPI, bool SP2, bool FP8 = false>
; __device__ __forceinline__ void gemm_phase(LAS unsigned char* lds, const Gemm g, const SchedT& S, const Epi& E, const int wid) {
;     ...
;             PG8_WAIT_V(8); PG8_WAIT_L(0); PG8_BAR; PG8_MMAP(0, 1, 0); PG8_BAR; PG8_SCHED;
;             PG8_LDA(At, 1, 1); PG8_S4;
;             PG8_WAIT_V(8); PG8_WAIT_L(0); PG8_BAR; PG8_MMAP(1, 1, 1); PG8_BAR; PG8_SCHED;
	v_mfma_scale_f32_16x16x128_f8f6f4 v[64:67], v[0:7], v[8:15], v[64:67], v152, v152 op_sel_hi:[0,0,0]
	v_mfma_scale_f32_16x16x128_f8f6f4 v[44:47], v[154:161], v[8:15], v[44:47], v152, v152 op_sel_hi:[0,0,0]
	v_mfma_scale_f32_16x16x128_f8f6f4 v[56:59], v[134:141], v[8:15], v[56:59], v152, v152 op_sel_hi:[0,0,0]
	v_mfma_scale_f32_16x16x128_f8f6f4 v[36:39], v[162:169], v[8:15], v[202:205], v152, v152 op_sel_hi:[0,0,0]
	v_mfma_scale_f32_16x16x128_f8f6f4 v[52:55], v[0:7], v[16:23], v[52:55], v152, v152 op_sel_hi:[0,0,0]
	v_mfma_scale_f32_16x16x128_f8f6f4 v[28:31], v[154:161], v[16:23], v[206:209], v152, v152 op_sel_hi:[0,0,0]
	v_mfma_scale_f32_16x16x128_f8f6f4 v[48:51], v[134:141], v[16:23], v[48:51], v152, v152 op_sel_hi:[0,0,0]
	v_mfma_scale_f32_16x16x128_f8f6f4 v[20:23], v[162:169], v[16:23], v[214:217], v152, v152 op_sel_hi:[0,0,0]
	v_mfma_scale_f32_16x16x128_f8f6f4 v[40:43], v[0:7], v[170:177], v[40:43], v152, v152 op_sel_hi:[0,0,0]
	v_mfma_scale_f32_16x16x128_f8f6f4 v[12:15], v[154:161], v[170:177], v[218:221], v152, v152 op_sel_hi:[0,0,0]
	v_mfma_scale_f32_16x16x128_f8f6f4 v[32:35], v[134:141], v[170:177], v[222:225], v152, v152 op_sel_hi:[0,0,0]
	v_mfma_scale_f32_16x16x128_f8f6f4 v[8:11], v[162:169], v[170:177], v[226:229], v152, v152 op_sel_hi:[0,0,0]
	v_mfma_scale_f32_16x16x128_f8f6f4 v[24:27], v[0:7], v[178:185], v[230:233], v152, v152 op_sel_hi:[0,0,0]
	v_mfma_scale_f32_16x16x128_f8f6f4 v[4:7], v[154:161], v[178:185], v[234:237], v152, v152 op_sel_hi:[0,0,0]
	v_mfma_scale_f32_16x16x128_f8f6f4 v[16:19], v[134:141], v[178:185], v[238:241], v152, v152 op_sel_hi:[0,0,0]
	v_mfma_scale_f32_16x16x128_f8f6f4 v[0:3], v[162:169], v[178:185], v[242:245], v152, v152 op_sel_hi:[0,0,0]
	s_barrier
	s_setprio 0
	s_add_u32 s52, s52, 0x100
	s_addc_u32 s53, s53, 0
	s_add_u32 s30, s30, 0x100
	s_addc_u32 s31, s31, 0
	s_cmp_ge_i32 s45, s20
	s_mov_b32 s47, s45
	s_cbranch_scc0 .LBB0_779
	v_pk_mul_f32 v[142:143], v[126:127], s[42:43] op_sel_hi:[1,0]
	v_pk_mul_f32 v[144:145], v[124:125], s[42:43] op_sel_hi:[1,0]
	v_pk_mul_f32 v[136:137], v[122:123], s[42:43] op_sel_hi:[1,0]
	v_pk_mul_f32 v[134:135], v[120:121], s[42:43] op_sel_hi:[1,0]
	v_pk_mul_f32 v[140:141], v[110:111], s[42:43] op_sel_hi:[1,0]
	v_pk_mul_f32 v[138:139], v[108:109], s[42:43] op_sel_hi:[1,0]
	v_pk_mul_f32 v[126:127], v[102:103], s[42:43] op_sel_hi:[1,0]
	v_pk_mul_f32 v[124:125], v[100:101], s[42:43] op_sel_hi:[1,0]
	v_pk_mul_f32 v[122:123], v[118:119], s[42:43] op_sel_hi:[1,0]
	v_pk_mul_f32 v[120:121], v[116:117], s[42:43] op_sel_hi:[1,0]
	v_pk_mul_f32 v[114:115], v[114:115], s[42:43] op_sel_hi:[1,0]
	v_pk_mul_f32 v[112:113], v[112:113], s[42:43] op_sel_hi:[1,0]
	v_pk_mul_f32 v[118:119], v[94:95], s[42:43] op_sel_hi:[1,0]
	v_pk_mul_f32 v[116:117], v[92:93], s[42:43] op_sel_hi:[1,0]
	v_pk_mul_f32 v[110:111], v[86:87], s[42:43] op_sel_hi:[1,0]
	v_pk_mul_f32 v[108:109], v[84:85], s[42:43] op_sel_hi:[1,0]
	v_pk_mul_f32 v[106:107], v[106:107], s[42:43] op_sel_hi:[1,0]
	v_pk_mul_f32 v[104:105], v[104:105], s[42:43] op_sel_hi:[1,0]
	v_pk_mul_f32 v[98:99], v[98:99], s[42:43] op_sel_hi:[1,0]
	v_pk_mul_f32 v[96:97], v[96:97], s[42:43] op_sel_hi:[1,0]
	v_pk_mul_f32 v[102:103], v[78:79], s[42:43] op_sel_hi:[1,0]
	v_pk_mul_f32 v[100:101], v[76:77], s[42:43] op_sel_hi:[1,0]
	v_pk_mul_f32 v[94:95], v[74:75], s[42:43] op_sel_hi:[1,0]
	v_pk_mul_f32 v[92:93], v[72:73], s[42:43] op_sel_hi:[1,0]
	v_pk_mul_f32 v[90:91], v[90:91], s[42:43] op_sel_hi:[1,0]
	v_pk_mul_f32 v[88:89], v[88:89], s[42:43] op_sel_hi:[1,0]
	v_pk_mul_f32 v[82:83], v[82:83], s[42:43] op_sel_hi:[1,0]
	v_pk_mul_f32 v[80:81], v[80:81], s[42:43] op_sel_hi:[1,0]
	v_pk_mul_f32 v[86:87], v[70:71], s[42:43] op_sel_hi:[1,0]
	v_pk_mul_f32 v[84:85], v[68:69], s[42:43] op_sel_hi:[1,0]
	v_pk_mul_f32 v[78:79], v[62:63], s[42:43] op_sel_hi:[1,0]
	v_pk_mul_f32 v[76:77], v[60:61], s[42:43] op_sel_hi:[1,0]
	v_pk_mul_f32 v[74:75], v[66:67], s[42:43] op_sel_hi:[1,0]
	v_pk_mul_f32 v[72:73], v[64:65], s[42:43] op_sel_hi:[1,0]
	v_pk_mul_f32 v[66:67], v[58:59], s[42:43] op_sel_hi:[1,0]
	v_pk_mul_f32 v[64:65], v[56:57], s[42:43] op_sel_hi:[1,0]
	v_pk_mul_f32 v[70:71], v[46:47], s[42:43] op_sel_hi:[1,0]
	v_pk_mul_f32 v[68:69], v[44:45], s[42:43] op_sel_hi:[1,0]
	v_pk_mul_f32 v[62:63], v[38:39], s[42:43] op_sel_hi:[1,0]
	v_pk_mul_f32 v[60:61], v[36:37], s[42:43] op_sel_hi:[1,0]
	v_pk_mul_f32 v[58:59], v[54:55], s[42:43] op_sel_hi:[1,0]
	v_pk_mul_f32 v[56:57], v[52:53], s[42:43] op_sel_hi:[1,0]
	v_pk_mul_f32 v[50:51], v[50:51], s[42:43] op_sel_hi:[1,0]
	v_pk_mul_f32 v[48:49], v[48:49], s[42:43] op_sel_hi:[1,0]
	v_pk_mul_f32 v[54:55], v[30:31], s[42:43] op_sel_hi:[1,0]
	v_pk_mul_f32 v[52:53], v[28:29], s[42:43] op_sel_hi:[1,0]
	v_pk_mul_f32 v[46:47], v[22:23], s[42:43] op_sel_hi:[1,0]
	v_pk_mul_f32 v[44:45], v[20:21], s[42:43] op_sel_hi:[1,0]
	v_pk_mul_f32 v[38:39], v[42:43], s[42:43] op_sel_hi:[1,0]
	v_pk_mul_f32 v[36:37], v[40:41], s[42:43] op_sel_hi:[1,0]
	v_pk_mul_f32 v[30:31], v[34:35], s[42:43] op_sel_hi:[1,0]
	v_pk_mul_f32 v[28:29], v[32:33], s[42:43] op_sel_hi:[1,0]
	v_pk_mul_f32 v[34:35], v[14:15], s[42:43] op_sel_hi:[1,0]
	v_pk_mul_f32 v[32:33], v[12:13], s[42:43] op_sel_hi:[1,0]
	v_pk_mul_f32 v[22:23], v[10:11], s[42:43] op_sel_hi:[1,0]
	v_pk_mul_f32 v[20:21], v[8:9], s[42:43] op_sel_hi:[1,0]
	v_pk_mul_f32 v[14:15], v[26:27], s[42:43] op_sel_hi:[1,0]
	v_pk_mul_f32 v[12:13], v[24:25], s[42:43] op_sel_hi:[1,0]
	v_pk_mul_f32 v[10:11], v[18:19], s[42:43] op_sel_hi:[1,0]
	v_pk_mul_f32 v[8:9], v[16:17], s[42:43] op_sel_hi:[1,0]
	v_pk_mul_f32 v[6:7], v[6:7], s[42:43] op_sel_hi:[1,0]
	v_pk_mul_f32 v[4:5], v[4:5], s[42:43] op_sel_hi:[1,0]
	v_pk_mul_f32 v[2:3], v[2:3], s[42:43] op_sel_hi:[1,0]
	v_pk_mul_f32 v[0:1], v[0:1], s[42:43] op_sel_hi:[1,0]
	s_and_b64 vcc, exec, s[96:97]
	s_cbranch_vccz .LBB0_782

; #define PG8_LDA(dst, b, h) do { if constexpr (FP8) { _Pragma("unroll") for (int m = 0; m < 4; ++m) dst##8[m] = PG8_LD8(PG8_SA(b, h), aoff, aoff1, m); } \
;         else { _Pragma("unroll") for (int m = 0; m < 4; ++m) _Pragma("unroll") for (int k = 0; k < 2; ++k) dst[m][k] = *(const LAS bf16x8*)(lds + PG8_SA(b, h) + (k ? aoff1 : aoff) + m * 2048); } } while (0)
; #define PG8_LDB(dst, b, h) do { if constexpr (FP8) { dst##8[0] = PG8_LD8(PG8_SB(b, h), boff, boff1, 0); dst##8[1] = PG8_LD8(PG8_SB(b, h), boff, boff1, 1); } \
;         else { _Pragma("unroll") for (int n = 0; n < 2; ++n) _Pragma("unroll") for (int k = 0; k < 2; ++k) dst[n][k] = *(const LAS bf16x8*)(lds + PG8_SB(b, h) + (k ? boff1 : boff) + n * 2048); } } while (0)
; #define PG8_WAIT_V(n) asm volatile("s_waitcnt vmcnt(" #n ")" ::: "memory")
; #define PG8_WAIT_L(n) asm volatile("s_waitcnt lgkmcnt(" #n ")" ::: "memory")
; #define PG8_BAR __builtin_amdgcn_s_barrier()
; #define PG8_SCHED __builtin_amdgcn_sched_barrier(0)
; #define PG8_S1 PG8_STAGE(PG8_SA(1, 1), a1 + hstepA, voffA)
; #define PG8_S2 do { PG8_STAGE(PG8_SB(0, 0), b2, voffB); PG8_STAGE(PG8_SB(0, 1), b2 + hstepB, voffB); PG8_STAGE(PG8_SA(0, 0), a2, voffA); } while (0)
; template <class Epi, class SchedT, bool ALIGN_EPI, bool SP2, bool FP8 = false>
; __device__ __forceinline__ void gemm_phase(LAS unsigned char* lds, const Gemm g, const SchedT& S, const Epi& E, const int wid) {
;     ...
;         for (int t = 0; t < nt; t += 2) {
;             const bool last = (t == nt - 2);
;             const char* a1 = cA + (size_t)(t + 1) * kstep;
;             const char* a2 = last ? nA : cA + (size_t)(t + 2) * kstep; const char* b2 = last ? nB : cB + (size_t)(t + 2) * kstep;
;             const char* a3 = a2 + kstep; const char* b3 = b2 + kstep;
;             if constexpr (SP2) {
;     ...
;             PG8_LDB(B0, 0, 0); PG8_LDB(B1, 0, 1); PG8_SCHED; PG8_LDA(At, 0, 0); PG8_S1;
;             PG8_WAIT_V(8); PG8_WAIT_L(0); PG8_BAR; PG8_MMAP(0, 0, 0); PG8_BAR; PG8_SCHED;
;             PG8_LDA(At, 0, 1); PG8_S2;
;             PG8_WAIT_V(8); PG8_WAIT_L(0); PG8_BAR; PG8_MMAP(1, 0, 1); PG8_BAR; PG8_SCHED;
.LBB0_899:
	ds_read_b128 v[128:131], v173
	ds_read_b128 v[132:135], v173 offset:1024
	ds_read_b128 v[136:139], v174
	ds_read_b128 v[140:143], v174 offset:1024
	ds_read_b128 v[150:153], v175
	ds_read_b128 v[154:157], v175 offset:1024
	ds_read_b128 v[158:161], v176
	ds_read_b128 v[162:165], v176 offset:1024
	s_add_i32 s35, s34, 2
	s_add_u32 s16, s48, 0xfffc0080
	s_addc_u32 s17, s49, -1
	s_cmp_eq_u32 s27, s34
	s_cselect_b32 s51, s15, s17
	s_cselect_b32 s50, s21, s16
	s_cselect_b32 s53, s24, s31
	s_cselect_b32 s52, s25, s30
	v_mov_b32_e32 v144, v168
	ds_read_b128 v[182:185], v177
	ds_read_b128 v[186:189], v177 offset:1024
	ds_read_b128 v[190:193], v177 offset:2048
	ds_read_b128 v[194:197], v177 offset:3072
	ds_read_b128 v[198:201], v177 offset:4096
	ds_read_b128 v[202:205], v177 offset:5120
	ds_read_b128 v[206:209], v177 offset:6144
	ds_read_b128 v[210:213], v177 offset:7168
	s_add_i32 m0, s87, 0xc000
	s_nop 0
	global_load_lds_dwordx4 v144, s[48:49]
	v_mov_b32_e32 v144, v170
	s_add_i32 m0, s87, 0xe000
	s_nop 0
	global_load_lds_dwordx4 v144, s[48:49]
	s_waitcnt vmcnt(8)
	s_waitcnt lgkmcnt(0)
	s_setprio 1
	s_barrier
	v_mfma_f32_16x16x32_bf16 v[124:127], v[128:131], v[182:185], v[124:127]
	v_mfma_f32_16x16x32_bf16 v[120:123], v[136:139], v[182:185], v[120:123]
	v_mfma_f32_16x16x32_bf16 v[104:107], v[136:139], v[190:193], v[104:107]
	v_mfma_f32_16x16x32_bf16 v[108:111], v[128:131], v[190:193], v[108:111]
	v_mfma_f32_16x16x32_bf16 v[92:95], v[128:131], v[198:201], v[92:95]
	v_mfma_f32_16x16x32_bf16 v[88:91], v[136:139], v[198:201], v[88:91]
	v_mfma_f32_16x16x32_bf16 v[72:75], v[136:139], v[206:209], v[72:75]
	v_mfma_f32_16x16x32_bf16 v[76:79], v[128:131], v[206:209], v[76:79]
	s_setprio 0
	s_setprio 1
	v_mfma_f32_16x16x32_bf16 v[124:127], v[132:135], v[186:189], v[124:127]
	v_mfma_f32_16x16x32_bf16 v[120:123], v[140:143], v[186:189], v[120:123]
	v_mfma_f32_16x16x32_bf16 v[104:107], v[140:143], v[194:197], v[104:107]
	v_mfma_f32_16x16x32_bf16 v[108:111], v[132:135], v[194:197], v[108:111]
	v_mfma_f32_16x16x32_bf16 v[92:95], v[132:135], v[202:205], v[92:95]
	v_mfma_f32_16x16x32_bf16 v[88:91], v[140:143], v[202:205], v[88:91]
	v_mfma_f32_16x16x32_bf16 v[72:75], v[140:143], v[210:213], v[72:75]
	v_mfma_f32_16x16x32_bf16 v[76:79], v[132:135], v[210:213], v[76:79]
	s_setprio 0
	s_setprio 1
	v_mfma_f32_16x16x32_bf16 v[116:119], v[150:153], v[182:185], v[116:119]
	v_mfma_f32_16x16x32_bf16 v[112:115], v[158:161], v[182:185], v[112:115]
	v_mfma_f32_16x16x32_bf16 v[96:99], v[158:161], v[190:193], v[96:99]
	v_mfma_f32_16x16x32_bf16 v[100:103], v[150:153], v[190:193], v[100:103]
	v_mfma_f32_16x16x32_bf16 v[84:87], v[150:153], v[198:201], v[84:87]
	v_mfma_f32_16x16x32_bf16 v[80:83], v[158:161], v[198:201], v[80:83]
	v_mfma_f32_16x16x32_bf16 v[64:67], v[158:161], v[206:209], v[64:67]
	v_mfma_f32_16x16x32_bf16 v[68:71], v[150:153], v[206:209], v[68:71]
	s_setprio 0
	s_setprio 1
	v_mfma_f32_16x16x32_bf16 v[116:119], v[154:157], v[186:189], v[116:119]
	v_mfma_f32_16x16x32_bf16 v[112:115], v[162:165], v[186:189], v[112:115]
	v_mfma_f32_16x16x32_bf16 v[96:99], v[162:165], v[194:197], v[96:99]
	v_mfma_f32_16x16x32_bf16 v[100:103], v[154:157], v[194:197], v[100:103]
	v_mfma_f32_16x16x32_bf16 v[84:87], v[154:157], v[202:205], v[84:87]
	v_mfma_f32_16x16x32_bf16 v[80:83], v[162:165], v[202:205], v[80:83]
	v_mfma_f32_16x16x32_bf16 v[64:67], v[162:165], v[210:213], v[64:67]
	v_mfma_f32_16x16x32_bf16 v[68:71], v[154:157], v[210:213], v[68:71]
	s_barrier
	s_setprio 0
	v_mov_b32_e32 v144, v169
	s_add_i32 s16, s94, s86
	ds_read_b128 v[182:185], v177 offset:16384
	ds_read_b128 v[186:189], v177 offset:17408
	ds_read_b128 v[190:193], v177 offset:18432
	ds_read_b128 v[194:197], v177 offset:19456
	ds_read_b128 v[198:201], v177 offset:20480
	ds_read_b128 v[202:205], v177 offset:21504
	ds_read_b128 v[206:209], v177 offset:22528
	ds_read_b128 v[210:213], v177 offset:23552
	s_mov_b32 m0, s16
	s_nop 0
	global_load_lds_dwordx4 v144, s[52:53]
	v_mov_b32_e32 v144, v171
	s_add_i32 m0, s16, 0x2000
	s_add_u32 s60, s52, 0x40000
	global_load_lds_dwordx4 v144, s[52:53]
	s_addc_u32 s61, s53, 0
	v_mov_b32_e32 v144, v169
	s_add_i32 s16, s95, s86
	s_mov_b32 m0, s16
	s_nop 0
	global_load_lds_dwordx4 v144, s[60:61]
	v_mov_b32_e32 v144, v171
	s_add_i32 m0, s16, 0x2000
	s_nop 0
	global_load_lds_dwordx4 v144, s[60:61]
	v_mov_b32_e32 v144, v168
	s_mov_b32 m0, s87
	s_nop 0
	global_load_lds_dwordx4 v144, s[50:51]
	v_mov_b32_e32 v144, v170
	s_mov_b32 m0, s88
	s_nop 0
	global_load_lds_dwordx4 v144, s[50:51]
	s_waitcnt vmcnt(8)
	s_waitcnt lgkmcnt(0)
	s_setprio 1
	s_barrier
; #define PG8_LDA(dst, b, h) do { if constexpr (FP8) { _Pragma("unroll") for (int m = 0; m < 4; ++m) dst##8[m] = PG8_LD8(PG8_SA(b, h), aoff, aoff1, m); } \
;         else { _Pragma("unroll") for (int m = 0; m < 4; ++m) _Pragma("unroll") for (int k = 0; k < 2; ++k) dst[m][k] = *(const LAS bf16x8*)(lds + PG8_SA(b, h) + (k ? aoff1 : aoff) + m * 2048); } } while (0)
; #define PG8_LDB(dst, b, h) do { if constexpr (FP8) { dst##8[0] = PG8_LD8(PG8_SB(b, h), boff, boff1, 0); dst##8[1] = PG8_LD8(PG8_SB(b, h), boff, boff1, 1); } \
;         else { _Pragma("unroll") for (int n = 0; n < 2; ++n) _Pragma("unroll") for (int k = 0; k < 2; ++k) dst[n][k] = *(const LAS bf16x8*)(lds + PG8_SB(b, h) + (k ? boff1 : boff) + n * 2048); } } while (0)
; #define PG8_WAIT_V(n) asm volatile("s_waitcnt vmcnt(" #n ")" ::: "memory")
; #define PG8_WAIT_L(n) asm volatile("s_waitcnt lgkmcnt(" #n ")" ::: "memory")
; #define PG8_BAR __builtin_amdgcn_s_barrier()
; #define PG8_SCHED __builtin_amdgcn_sched_barrier(0)
; #define PG8_S3 PG8_STAGE(PG8_SA(0, 1), a2 + hstepA, voffA)
; #define PG8_S4 do { PG8_STAGE(PG8_SB(1, 0), b3, voffB); PG8_STAGE(PG8_SB(1, 1), b3 + hstepB, voffB); PG8_STAGE(PG8_SA(1, 0), a3, voffA); } while (0)
; template <class Epi, class SchedT, bool ALIGN_EPI, bool SP2, bool FP8 = false>
; __device__ __forceinline__ void gemm_phase(LAS unsigned char* lds, const Gemm g, const SchedT& S, const Epi& E, const int wid) {
;     ...
;             PG8_WAIT_V(8); PG8_WAIT_L(0); PG8_BAR; PG8_MMAP(1, 0, 1); PG8_BAR; PG8_SCHED;
;             PG8_LDB(B0, 1, 0); PG8_LDB(B1, 1, 1); PG8_SCHED; PG8_LDA(At, 1, 0); PG8_S3;
;             PG8_WAIT_V(8); PG8_WAIT_L(0); PG8_BAR; PG8_MMAP(0, 1, 0); PG8_BAR; PG8_SCHED;
;             PG8_LDA(At, 1, 1); PG8_S4;
	v_mfma_f32_16x16x32_bf16 v[60:63], v[128:131], v[182:185], v[60:63]
	v_mfma_f32_16x16x32_bf16 v[56:59], v[136:139], v[182:185], v[56:59]
	v_mfma_f32_16x16x32_bf16 v[40:43], v[136:139], v[190:193], v[40:43]
	v_mfma_f32_16x16x32_bf16 v[44:47], v[128:131], v[190:193], v[44:47]
	v_mfma_f32_16x16x32_bf16 v[28:31], v[128:131], v[198:201], v[28:31]
	v_mfma_f32_16x16x32_bf16 v[24:27], v[136:139], v[198:201], v[24:27]
	v_mfma_f32_16x16x32_bf16 v[8:11], v[136:139], v[206:209], v[8:11]
	v_mfma_f32_16x16x32_bf16 v[12:15], v[128:131], v[206:209], v[12:15]
	s_setprio 0
	s_setprio 1
	v_mfma_f32_16x16x32_bf16 v[60:63], v[132:135], v[186:189], v[60:63]
	v_mfma_f32_16x16x32_bf16 v[56:59], v[140:143], v[186:189], v[56:59]
	v_mfma_f32_16x16x32_bf16 v[40:43], v[140:143], v[194:197], v[40:43]
	v_mfma_f32_16x16x32_bf16 v[44:47], v[132:135], v[194:197], v[44:47]
	v_mfma_f32_16x16x32_bf16 v[28:31], v[132:135], v[202:205], v[28:31]
	v_mfma_f32_16x16x32_bf16 v[24:27], v[140:143], v[202:205], v[24:27]
	v_mfma_f32_16x16x32_bf16 v[8:11], v[140:143], v[210:213], v[8:11]
	v_mfma_f32_16x16x32_bf16 v[12:15], v[132:135], v[210:213], v[12:15]
	s_setprio 0
	s_setprio 1
	v_mfma_f32_16x16x32_bf16 v[52:55], v[150:153], v[182:185], v[52:55]
	v_mfma_f32_16x16x32_bf16 v[48:51], v[158:161], v[182:185], v[48:51]
	v_mfma_f32_16x16x32_bf16 v[32:35], v[158:161], v[190:193], v[32:35]
	v_mfma_f32_16x16x32_bf16 v[36:39], v[150:153], v[190:193], v[36:39]
	v_mfma_f32_16x16x32_bf16 v[20:23], v[150:153], v[198:201], v[20:23]
	v_mfma_f32_16x16x32_bf16 v[16:19], v[158:161], v[198:201], v[16:19]
	v_mfma_f32_16x16x32_bf16 v[0:3], v[158:161], v[206:209], v[0:3]
	v_mfma_f32_16x16x32_bf16 v[4:7], v[150:153], v[206:209], v[4:7]
	s_setprio 0
	s_setprio 1
	v_mfma_f32_16x16x32_bf16 v[52:55], v[154:157], v[186:189], v[52:55]
	v_mfma_f32_16x16x32_bf16 v[48:51], v[162:165], v[186:189], v[48:51]
	v_mfma_f32_16x16x32_bf16 v[32:35], v[162:165], v[194:197], v[32:35]
	v_mfma_f32_16x16x32_bf16 v[36:39], v[154:157], v[194:197], v[36:39]
	v_mfma_f32_16x16x32_bf16 v[20:23], v[154:157], v[202:205], v[20:23]
	v_mfma_f32_16x16x32_bf16 v[16:19], v[162:165], v[202:205], v[16:19]
	v_mfma_f32_16x16x32_bf16 v[0:3], v[162:165], v[210:213], v[0:3]
	v_mfma_f32_16x16x32_bf16 v[4:7], v[154:157], v[210:213], v[4:7]
	s_barrier
	s_setprio 0
	s_add_i32 s16, 0, 0x18000
	s_add_i32 s17, 0, 0x1c000
	v_add_u32_e32 v132, s16, v172
	v_add_u32_e32 v144, s17, v172
	ds_read_b128 v[128:131], v132
	ds_read_b128 v[132:135], v132 offset:1024
	ds_read_b128 v[136:139], v178
	ds_read_b128 v[140:143], v178 offset:1024
	ds_read_b128 v[150:153], v144
	ds_read_b128 v[154:157], v144 offset:1024
	ds_read_b128 v[158:161], v179
	ds_read_b128 v[162:165], v179 offset:1024
	s_add_u32 s60, s50, 0x40000
	v_mov_b32_e32 v144, v168
	s_mov_b32 m0, s89
	ds_read_b128 v[182:185], v177 offset:32768
	ds_read_b128 v[186:189], v177 offset:33792
	ds_read_b128 v[190:193], v177 offset:34816
	ds_read_b128 v[194:197], v177 offset:35840
	ds_read_b128 v[198:201], v177 offset:36864
	ds_read_b128 v[202:205], v177 offset:37888
	ds_read_b128 v[206:209], v177 offset:38912
	ds_read_b128 v[210:213], v177 offset:39936
	s_addc_u32 s61, s51, 0
	s_nop 0
	global_load_lds_dwordx4 v144, s[60:61]
	v_mov_b32_e32 v144, v170
	s_mov_b32 m0, s90
	s_nop 0
	global_load_lds_dwordx4 v144, s[60:61]
	s_waitcnt vmcnt(8)
	s_waitcnt lgkmcnt(0)
	s_setprio 1
	s_barrier
	v_mfma_f32_16x16x32_bf16 v[124:127], v[128:131], v[182:185], v[124:127]
	v_mfma_f32_16x16x32_bf16 v[120:123], v[136:139], v[182:185], v[120:123]
	v_mfma_f32_16x16x32_bf16 v[104:107], v[136:139], v[190:193], v[104:107]
	v_mfma_f32_16x16x32_bf16 v[108:111], v[128:131], v[190:193], v[108:111]
	v_mfma_f32_16x16x32_bf16 v[92:95], v[128:131], v[198:201], v[92:95]
	v_mfma_f32_16x16x32_bf16 v[88:91], v[136:139], v[198:201], v[88:91]
	v_mfma_f32_16x16x32_bf16 v[72:75], v[136:139], v[206:209], v[72:75]
	v_mfma_f32_16x16x32_bf16 v[76:79], v[128:131], v[206:209], v[76:79]
	s_setprio 0
	s_setprio 1
	v_mfma_f32_16x16x32_bf16 v[124:127], v[132:135], v[186:189], v[124:127]
	v_mfma_f32_16x16x32_bf16 v[120:123], v[140:143], v[186:189], v[120:123]
	v_mfma_f32_16x16x32_bf16 v[104:107], v[140:143], v[194:197], v[104:107]
	v_mfma_f32_16x16x32_bf16 v[108:111], v[132:135], v[194:197], v[108:111]
	v_mfma_f32_16x16x32_bf16 v[92:95], v[132:135], v[202:205], v[92:95]
	v_mfma_f32_16x16x32_bf16 v[88:91], v[140:143], v[202:205], v[88:91]
	v_mfma_f32_16x16x32_bf16 v[72:75], v[140:143], v[210:213], v[72:75]
	v_mfma_f32_16x16x32_bf16 v[76:79], v[132:135], v[210:213], v[76:79]
	s_setprio 0
	s_setprio 1
	v_mfma_f32_16x16x32_bf16 v[116:119], v[150:153], v[182:185], v[116:119]
	v_mfma_f32_16x16x32_bf16 v[112:115], v[158:161], v[182:185], v[112:115]
	v_mfma_f32_16x16x32_bf16 v[96:99], v[158:161], v[190:193], v[96:99]
	v_mfma_f32_16x16x32_bf16 v[100:103], v[150:153], v[190:193], v[100:103]
	v_mfma_f32_16x16x32_bf16 v[84:87], v[150:153], v[198:201], v[84:87]
	v_mfma_f32_16x16x32_bf16 v[80:83], v[158:161], v[198:201], v[80:83]
	v_mfma_f32_16x16x32_bf16 v[64:67], v[158:161], v[206:209], v[64:67]
	v_mfma_f32_16x16x32_bf16 v[68:71], v[150:153], v[206:209], v[68:71]
	s_setprio 0
	s_setprio 1
	v_mfma_f32_16x16x32_bf16 v[116:119], v[154:157], v[186:189], v[116:119]
	v_mfma_f32_16x16x32_bf16 v[112:115], v[162:165], v[186:189], v[112:115]
	v_mfma_f32_16x16x32_bf16 v[96:99], v[162:165], v[194:197], v[96:99]
	v_mfma_f32_16x16x32_bf16 v[100:103], v[154:157], v[194:197], v[100:103]
	v_mfma_f32_16x16x32_bf16 v[84:87], v[154:157], v[202:205], v[84:87]
	v_mfma_f32_16x16x32_bf16 v[80:83], v[162:165], v[202:205], v[80:83]
	v_mfma_f32_16x16x32_bf16 v[64:67], v[162:165], v[210:213], v[64:67]
	v_mfma_f32_16x16x32_bf16 v[68:71], v[154:157], v[210:213], v[68:71]
	s_barrier
; #define PG8_LDA(dst, b, h) do { if constexpr (FP8) { _Pragma("unroll") for (int m = 0; m < 4; ++m) dst##8[m] = PG8_LD8(PG8_SA(b, h), aoff, aoff1, m); } \
;         else { _Pragma("unroll") for (int m = 0; m < 4; ++m) _Pragma("unroll") for (int k = 0; k < 2; ++k) dst[m][k] = *(const LAS bf16x8*)(lds + PG8_SA(b, h) + (k ? aoff1 : aoff) + m * 2048); } } while (0)
; #define PG8_WAIT_V(n) asm volatile("s_waitcnt vmcnt(" #n ")" ::: "memory")
; #define PG8_WAIT_L(n) asm volatile("s_waitcnt lgkmcnt(" #n ")" ::: "memory")
; #define PG8_BAR __builtin_amdgcn_s_barrier()
; #define PG8_SCHED __builtin_amdgcn_sched_barrier(0)
; #define PG8_S4 do { PG8_STAGE(PG8_SB(1, 0), b3, voffB); PG8_STAGE(PG8_SB(1, 1), b3 + hstepB, voffB); PG8_STAGE(PG8_SA(1, 0), a3, voffA); } while (0)
; template <class Epi, class SchedT, bool ALIGN_EPI, bool SP2, bool FP8 = false>
; __device__ __forceinline__ void gemm_phase(LAS unsigned char* lds, const Gemm g, const SchedT& S, const Epi& E, const int wid) {
;     ...
;             PG8_WAIT_V(8); PG8_WAIT_L(0); PG8_BAR; PG8_MMAP(0, 1, 0); PG8_BAR; PG8_SCHED;
;             PG8_LDA(At, 1, 1); PG8_S4;
;             PG8_WAIT_V(8); PG8_WAIT_L(0); PG8_BAR; PG8_MMAP(1, 1, 1); PG8_BAR; PG8_SCHED;
	s_setprio 0
	v_mov_b32_e32 v144, v169
	ds_read_b128 v[182:185], v177 offset:49152
	ds_read_b128 v[186:189], v177 offset:50176
	ds_read_b128 v[190:193], v177 offset:51200
	ds_read_b128 v[194:197], v177 offset:52224
	ds_read_b128 v[198:201], v177 offset:53248
	ds_read_b128 v[202:205], v177 offset:54272
	ds_read_b128 v[206:209], v177 offset:55296
	ds_read_b128 v[210:213], v177 offset:56320
	s_add_i32 s16, s16, s86
	v_lshl_add_u64 v[166:167], s[52:53], 0, v[144:145]
	v_lshl_add_u64 v[166:167], v[166:167], 0, s[6:7]
	s_mov_b32 m0, s16
	v_mov_b32_e32 v144, v171
	global_load_lds_dwordx4 v[166:167], off
	s_add_i32 m0, s16, 0x2000
	s_nop 0
	v_lshl_add_u64 v[166:167], s[52:53], 0, v[144:145]
	s_add_u32 s52, s52, 0x40080
	v_lshl_add_u64 v[166:167], v[166:167], 0, s[6:7]
	s_addc_u32 s53, s53, 0
	v_mov_b32_e32 v144, v169
	s_add_i32 s16, s17, s86
	global_load_lds_dwordx4 v[166:167], off
	s_mov_b32 m0, s16
	s_nop 0
	global_load_lds_dwordx4 v144, s[52:53]
	v_mov_b32_e32 v144, v171
	s_add_i32 m0, s16, 0x2000
	s_nop 0
	global_load_lds_dwordx4 v144, s[52:53]
	v_mov_b32_e32 v144, v168
	s_mov_b32 m0, s92
	v_lshl_add_u64 v[166:167], s[50:51], 0, v[144:145]
	v_lshl_add_u64 v[166:167], v[166:167], 0, s[6:7]
	v_mov_b32_e32 v144, v170
	global_load_lds_dwordx4 v[166:167], off
	s_mov_b32 m0, s93
	v_lshl_add_u64 v[166:167], s[50:51], 0, v[144:145]
	v_lshl_add_u64 v[166:167], v[166:167], 0, s[6:7]
	global_load_lds_dwordx4 v[166:167], off
	s_waitcnt vmcnt(8)
	s_waitcnt lgkmcnt(0)
	s_setprio 1
	s_barrier
	v_mfma_f32_16x16x32_bf16 v[60:63], v[128:131], v[182:185], v[60:63]
	v_mfma_f32_16x16x32_bf16 v[56:59], v[136:139], v[182:185], v[56:59]
	v_mfma_f32_16x16x32_bf16 v[40:43], v[136:139], v[190:193], v[40:43]
	v_mfma_f32_16x16x32_bf16 v[44:47], v[128:131], v[190:193], v[44:47]
	v_mfma_f32_16x16x32_bf16 v[28:31], v[128:131], v[198:201], v[28:31]
	v_mfma_f32_16x16x32_bf16 v[24:27], v[136:139], v[198:201], v[24:27]
	v_mfma_f32_16x16x32_bf16 v[8:11], v[136:139], v[206:209], v[8:11]
	v_mfma_f32_16x16x32_bf16 v[12:15], v[128:131], v[206:209], v[12:15]
	s_setprio 0
	s_setprio 1
	v_mfma_f32_16x16x32_bf16 v[60:63], v[132:135], v[186:189], v[60:63]
	v_mfma_f32_16x16x32_bf16 v[56:59], v[140:143], v[186:189], v[56:59]
	v_mfma_f32_16x16x32_bf16 v[40:43], v[140:143], v[194:197], v[40:43]
	v_mfma_f32_16x16x32_bf16 v[44:47], v[132:135], v[194:197], v[44:47]
	v_mfma_f32_16x16x32_bf16 v[28:31], v[132:135], v[202:205], v[28:31]
	v_mfma_f32_16x16x32_bf16 v[24:27], v[140:143], v[202:205], v[24:27]
	v_mfma_f32_16x16x32_bf16 v[8:11], v[140:143], v[210:213], v[8:11]
	v_mfma_f32_16x16x32_bf16 v[12:15], v[132:135], v[210:213], v[12:15]
	s_setprio 0
	s_setprio 1
	v_mfma_f32_16x16x32_bf16 v[52:55], v[150:153], v[182:185], v[52:55]
	v_mfma_f32_16x16x32_bf16 v[48:51], v[158:161], v[182:185], v[48:51]
	v_mfma_f32_16x16x32_bf16 v[32:35], v[158:161], v[190:193], v[32:35]
	v_mfma_f32_16x16x32_bf16 v[36:39], v[150:153], v[190:193], v[36:39]
	v_mfma_f32_16x16x32_bf16 v[20:23], v[150:153], v[198:201], v[20:23]
	v_mfma_f32_16x16x32_bf16 v[16:19], v[158:161], v[198:201], v[16:19]
	v_mfma_f32_16x16x32_bf16 v[0:3], v[158:161], v[206:209], v[0:3]
	v_mfma_f32_16x16x32_bf16 v[4:7], v[150:153], v[206:209], v[4:7]
	s_setprio 0
	s_setprio 1
	v_mfma_f32_16x16x32_bf16 v[52:55], v[154:157], v[186:189], v[52:55]
	v_mfma_f32_16x16x32_bf16 v[48:51], v[162:165], v[186:189], v[48:51]
	v_mfma_f32_16x16x32_bf16 v[32:35], v[162:165], v[194:197], v[32:35]
	v_mfma_f32_16x16x32_bf16 v[36:39], v[154:157], v[194:197], v[36:39]
	v_mfma_f32_16x16x32_bf16 v[20:23], v[154:157], v[202:205], v[20:23]
	v_mfma_f32_16x16x32_bf16 v[16:19], v[162:165], v[202:205], v[16:19]
	v_mfma_f32_16x16x32_bf16 v[0:3], v[162:165], v[210:213], v[0:3]
	v_mfma_f32_16x16x32_bf16 v[4:7], v[154:157], v[210:213], v[4:7]
	s_barrier
	s_setprio 0
	s_add_u32 s48, s48, 0x100
	s_addc_u32 s49, s49, 0
	s_add_u32 s30, s30, 0x100
	s_addc_u32 s31, s31, 0
	s_cmp_ge_i32 s35, s20
	s_mov_b32 s34, s35
	s_cbranch_scc0 .LBB0_899
	s_branch .LBB0_894

; #define PG8_LDA(dst, b, h) do { if constexpr (FP8) { _Pragma("unroll") for (int m = 0; m < 4; ++m) dst##8[m] = PG8_LD8(PG8_SA(b, h), aoff, aoff1, m); } \
;         else { _Pragma("unroll") for (int m = 0; m < 4; ++m) _Pragma("unroll") for (int k = 0; k < 2; ++k) dst[m][k] = *(const LAS bf16x8*)(lds + PG8_SA(b, h) + (k ? aoff1 : aoff) + m * 2048); } } while (0)
; #define PG8_LDB(dst, b, h) do { if constexpr (FP8) { dst##8[0] = PG8_LD8(PG8_SB(b, h), boff, boff1, 0); dst##8[1] = PG8_LD8(PG8_SB(b, h), boff, boff1, 1); } \
;         else { _Pragma("unroll") for (int n = 0; n < 2; ++n) _Pragma("unroll") for (int k = 0; k < 2; ++k) dst[n][k] = *(const LAS bf16x8*)(lds + PG8_SB(b, h) + (k ? boff1 : boff) + n * 2048); } } while (0)
; #define PG8_WAIT_V(n) asm volatile("s_waitcnt vmcnt(" #n ")" ::: "memory")
; #define PG8_WAIT_L(n) asm volatile("s_waitcnt lgkmcnt(" #n ")" ::: "memory")
; #define PG8_BAR __builtin_amdgcn_s_barrier()
; #define PG8_SCHED __builtin_amdgcn_sched_barrier(0)
; #define PG8_S1 PG8_STAGE(PG8_SA(1, 1), a1 + hstepA, voffA)
; #define PG8_S2 do { PG8_STAGE(PG8_SB(0, 0), b2, voffB); PG8_STAGE(PG8_SB(0, 1), b2 + hstepB, voffB); PG8_STAGE(PG8_SA(0, 0), a2, voffA); } while (0)
; template <class Epi, class SchedT, bool ALIGN_EPI, bool SP2, bool FP8 = false>
; __device__ __forceinline__ void gemm_phase(LAS unsigned char* lds, const Gemm g, const SchedT& S, const Epi& E, const int wid) {
;     ...
;         for (int t = 0; t < nt; t += 2) {
;             const bool last = (t == nt - 2);
;             const char* a1 = cA + (size_t)(t + 1) * kstep;
;             const char* a2 = last ? nA : cA + (size_t)(t + 2) * kstep; const char* b2 = last ? nB : cB + (size_t)(t + 2) * kstep;
;             const char* a3 = a2 + kstep; const char* b3 = b2 + kstep;
;             if constexpr (SP2) {
;     ...
;             PG8_LDB(B0, 0, 0); PG8_LDB(B1, 0, 1); PG8_SCHED; PG8_LDA(At, 0, 0); PG8_S1;
;             PG8_WAIT_V(8); PG8_WAIT_L(0); PG8_BAR; PG8_MMAP(0, 0, 0); PG8_BAR; PG8_SCHED;
;             PG8_LDA(At, 0, 1); PG8_S2;
;             PG8_WAIT_V(8); PG8_WAIT_L(0); PG8_BAR; PG8_MMAP(1, 0, 1); PG8_BAR; PG8_SCHED;
.LBB0_970:
	ds_read_b128 v[134:137], v175
	ds_read_b128 v[138:141], v175 offset:1024
	ds_read_b128 v[142:145], v176
	ds_read_b128 v[146:149], v176 offset:1024
	ds_read_b128 v[150:153], v177
	ds_read_b128 v[154:157], v177 offset:1024
	ds_read_b128 v[158:161], v178
	ds_read_b128 v[162:165], v178 offset:1024
	s_add_i32 s48, s34, 2
	s_add_u32 s16, s24, 0xfff00080
	s_addc_u32 s17, s25, -1
	s_cmp_eq_u32 s45, s34
	s_cselect_b32 s34, s15, s16
	s_cselect_b32 s35, s13, s17
	s_cselect_b32 s39, s27, s47
	s_cselect_b32 s38, s31, s46
	v_mov_b32_e32 v128, v172
	ds_read_b128 v[166:169], v179
	ds_read_b128 v[184:187], v179 offset:1024
	ds_read_b128 v[188:191], v179 offset:2048
	ds_read_b128 v[192:195], v179 offset:3072
	ds_read_b128 v[196:199], v179 offset:4096
	ds_read_b128 v[200:203], v179 offset:5120
	ds_read_b128 v[204:207], v179 offset:6144
	ds_read_b128 v[208:211], v179 offset:7168
	s_add_i32 m0, s87, 0xc000
	s_nop 0
	global_load_lds_dwordx4 v128, s[24:25]
	v_mov_b32_e32 v128, v173
	s_add_i32 m0, s87, 0xe000
	s_nop 0
	global_load_lds_dwordx4 v128, s[24:25]
	s_waitcnt vmcnt(8)
	s_waitcnt lgkmcnt(0)
	s_setprio 1
	s_barrier
	v_mfma_f32_16x16x32_bf16 v[124:127], v[134:137], v[166:169], v[124:127]
	v_mfma_f32_16x16x32_bf16 v[120:123], v[142:145], v[166:169], v[120:123]
	v_mfma_f32_16x16x32_bf16 v[104:107], v[142:145], v[188:191], v[104:107]
	v_mfma_f32_16x16x32_bf16 v[108:111], v[134:137], v[188:191], v[108:111]
	v_mfma_f32_16x16x32_bf16 v[92:95], v[134:137], v[196:199], v[92:95]
	v_mfma_f32_16x16x32_bf16 v[88:91], v[142:145], v[196:199], v[88:91]
	v_mfma_f32_16x16x32_bf16 v[72:75], v[142:145], v[204:207], v[72:75]
	v_mfma_f32_16x16x32_bf16 v[76:79], v[134:137], v[204:207], v[76:79]
	s_setprio 0
	s_setprio 1
	v_mfma_f32_16x16x32_bf16 v[124:127], v[138:141], v[184:187], v[124:127]
	v_mfma_f32_16x16x32_bf16 v[120:123], v[146:149], v[184:187], v[120:123]
	v_mfma_f32_16x16x32_bf16 v[104:107], v[146:149], v[192:195], v[104:107]
	v_mfma_f32_16x16x32_bf16 v[108:111], v[138:141], v[192:195], v[108:111]
	v_mfma_f32_16x16x32_bf16 v[92:95], v[138:141], v[200:203], v[92:95]
	v_mfma_f32_16x16x32_bf16 v[88:91], v[146:149], v[200:203], v[88:91]
	v_mfma_f32_16x16x32_bf16 v[72:75], v[146:149], v[208:211], v[72:75]
	v_mfma_f32_16x16x32_bf16 v[76:79], v[138:141], v[208:211], v[76:79]
	s_setprio 0
	s_setprio 1
	v_mfma_f32_16x16x32_bf16 v[116:119], v[150:153], v[166:169], v[116:119]
	v_mfma_f32_16x16x32_bf16 v[112:115], v[158:161], v[166:169], v[112:115]
	v_mfma_f32_16x16x32_bf16 v[96:99], v[158:161], v[188:191], v[96:99]
	v_mfma_f32_16x16x32_bf16 v[100:103], v[150:153], v[188:191], v[100:103]
	v_mfma_f32_16x16x32_bf16 v[84:87], v[150:153], v[196:199], v[84:87]
	v_mfma_f32_16x16x32_bf16 v[80:83], v[158:161], v[196:199], v[80:83]
	v_mfma_f32_16x16x32_bf16 v[64:67], v[158:161], v[204:207], v[64:67]
	v_mfma_f32_16x16x32_bf16 v[68:71], v[150:153], v[204:207], v[68:71]
	s_setprio 0
	s_setprio 1
	v_mfma_f32_16x16x32_bf16 v[116:119], v[154:157], v[184:187], v[116:119]
	v_mfma_f32_16x16x32_bf16 v[112:115], v[162:165], v[184:187], v[112:115]
	v_mfma_f32_16x16x32_bf16 v[96:99], v[162:165], v[192:195], v[96:99]
	v_mfma_f32_16x16x32_bf16 v[100:103], v[154:157], v[192:195], v[100:103]
	v_mfma_f32_16x16x32_bf16 v[84:87], v[154:157], v[200:203], v[84:87]
	v_mfma_f32_16x16x32_bf16 v[80:83], v[162:165], v[200:203], v[80:83]
	v_mfma_f32_16x16x32_bf16 v[64:67], v[162:165], v[208:211], v[64:67]
	v_mfma_f32_16x16x32_bf16 v[68:71], v[154:157], v[208:211], v[68:71]
	s_barrier
	s_setprio 0
	v_mov_b32_e32 v128, v172
	s_add_i32 s16, s94, s86
	ds_read_b128 v[166:169], v179 offset:16384
	ds_read_b128 v[184:187], v179 offset:17408
	ds_read_b128 v[188:191], v179 offset:18432
	ds_read_b128 v[192:195], v179 offset:19456
	ds_read_b128 v[196:199], v179 offset:20480
	ds_read_b128 v[200:203], v179 offset:21504
	ds_read_b128 v[204:207], v179 offset:22528
	ds_read_b128 v[208:211], v179 offset:23552
	s_mov_b32 m0, s16
	s_nop 0
	global_load_lds_dwordx4 v128, s[38:39]
	v_mov_b32_e32 v128, v173
	s_add_i32 m0, s16, 0x2000
	s_add_u32 s50, s38, 0x100000
	global_load_lds_dwordx4 v128, s[38:39]
	s_addc_u32 s51, s39, 0
	v_mov_b32_e32 v128, v172
	s_add_i32 s16, s95, s86
	s_mov_b32 m0, s16
	s_nop 0
	global_load_lds_dwordx4 v128, s[50:51]
	v_mov_b32_e32 v128, v173
	s_add_i32 m0, s16, 0x2000
	s_nop 0
	global_load_lds_dwordx4 v128, s[50:51]
	v_mov_b32_e32 v128, v172
	s_mov_b32 m0, s87
	s_nop 0
	global_load_lds_dwordx4 v128, s[34:35]
	v_mov_b32_e32 v128, v173
	s_mov_b32 m0, s88
	s_nop 0
	global_load_lds_dwordx4 v128, s[34:35]
	s_waitcnt vmcnt(8)
	s_waitcnt lgkmcnt(0)
	s_setprio 1
	s_barrier
; #define PG8_LDA(dst, b, h) do { if constexpr (FP8) { _Pragma("unroll") for (int m = 0; m < 4; ++m) dst##8[m] = PG8_LD8(PG8_SA(b, h), aoff, aoff1, m); } \
;         else { _Pragma("unroll") for (int m = 0; m < 4; ++m) _Pragma("unroll") for (int k = 0; k < 2; ++k) dst[m][k] = *(const LAS bf16x8*)(lds + PG8_SA(b, h) + (k ? aoff1 : aoff) + m * 2048); } } while (0)
; #define PG8_LDB(dst, b, h) do { if constexpr (FP8) { dst##8[0] = PG8_LD8(PG8_SB(b, h), boff, boff1, 0); dst##8[1] = PG8_LD8(PG8_SB(b, h), boff, boff1, 1); } \
;         else { _Pragma("unroll") for (int n = 0; n < 2; ++n) _Pragma("unroll") for (int k = 0; k < 2; ++k) dst[n][k] = *(const LAS bf16x8*)(lds + PG8_SB(b, h) + (k ? boff1 : boff) + n * 2048); } } while (0)
; #define PG8_WAIT_V(n) asm volatile("s_waitcnt vmcnt(" #n ")" ::: "memory")
; #define PG8_WAIT_L(n) asm volatile("s_waitcnt lgkmcnt(" #n ")" ::: "memory")
; #define PG8_BAR __builtin_amdgcn_s_barrier()
; #define PG8_SCHED __builtin_amdgcn_sched_barrier(0)
; #define PG8_S3 PG8_STAGE(PG8_SA(0, 1), a2 + hstepA, voffA)
; #define PG8_S4 do { PG8_STAGE(PG8_SB(1, 0), b3, voffB); PG8_STAGE(PG8_SB(1, 1), b3 + hstepB, voffB); PG8_STAGE(PG8_SA(1, 0), a3, voffA); } while (0)
; template <class Epi, class SchedT, bool ALIGN_EPI, bool SP2, bool FP8 = false>
; __device__ __forceinline__ void gemm_phase(LAS unsigned char* lds, const Gemm g, const SchedT& S, const Epi& E, const int wid) {
;     ...
;             PG8_WAIT_V(8); PG8_WAIT_L(0); PG8_BAR; PG8_MMAP(1, 0, 1); PG8_BAR; PG8_SCHED;
;             PG8_LDB(B0, 1, 0); PG8_LDB(B1, 1, 1); PG8_SCHED; PG8_LDA(At, 1, 0); PG8_S3;
;             PG8_WAIT_V(8); PG8_WAIT_L(0); PG8_BAR; PG8_MMAP(0, 1, 0); PG8_BAR; PG8_SCHED;
;             PG8_LDA(At, 1, 1); PG8_S4;
	v_mfma_f32_16x16x32_bf16 v[60:63], v[134:137], v[166:169], v[60:63]
	v_mfma_f32_16x16x32_bf16 v[56:59], v[142:145], v[166:169], v[56:59]
	v_mfma_f32_16x16x32_bf16 v[40:43], v[142:145], v[188:191], v[40:43]
	v_mfma_f32_16x16x32_bf16 v[44:47], v[134:137], v[188:191], v[44:47]
	v_mfma_f32_16x16x32_bf16 v[28:31], v[134:137], v[196:199], v[28:31]
	v_mfma_f32_16x16x32_bf16 v[24:27], v[142:145], v[196:199], v[24:27]
	v_mfma_f32_16x16x32_bf16 v[8:11], v[142:145], v[204:207], v[8:11]
	v_mfma_f32_16x16x32_bf16 v[12:15], v[134:137], v[204:207], v[12:15]
	s_setprio 0
	s_setprio 1
	v_mfma_f32_16x16x32_bf16 v[60:63], v[138:141], v[184:187], v[60:63]
	v_mfma_f32_16x16x32_bf16 v[56:59], v[146:149], v[184:187], v[56:59]
	v_mfma_f32_16x16x32_bf16 v[40:43], v[146:149], v[192:195], v[40:43]
	v_mfma_f32_16x16x32_bf16 v[44:47], v[138:141], v[192:195], v[44:47]
	v_mfma_f32_16x16x32_bf16 v[28:31], v[138:141], v[200:203], v[28:31]
	v_mfma_f32_16x16x32_bf16 v[24:27], v[146:149], v[200:203], v[24:27]
	v_mfma_f32_16x16x32_bf16 v[8:11], v[146:149], v[208:211], v[8:11]
	v_mfma_f32_16x16x32_bf16 v[12:15], v[138:141], v[208:211], v[12:15]
	s_setprio 0
	s_setprio 1
	v_mfma_f32_16x16x32_bf16 v[52:55], v[150:153], v[166:169], v[52:55]
	v_mfma_f32_16x16x32_bf16 v[48:51], v[158:161], v[166:169], v[48:51]
	v_mfma_f32_16x16x32_bf16 v[32:35], v[158:161], v[188:191], v[32:35]
	v_mfma_f32_16x16x32_bf16 v[36:39], v[150:153], v[188:191], v[36:39]
	v_mfma_f32_16x16x32_bf16 v[20:23], v[150:153], v[196:199], v[20:23]
	v_mfma_f32_16x16x32_bf16 v[16:19], v[158:161], v[196:199], v[16:19]
	v_mfma_f32_16x16x32_bf16 v[0:3], v[158:161], v[204:207], v[0:3]
	v_mfma_f32_16x16x32_bf16 v[4:7], v[150:153], v[204:207], v[4:7]
	s_setprio 0
	s_setprio 1
	v_mfma_f32_16x16x32_bf16 v[52:55], v[154:157], v[184:187], v[52:55]
	v_mfma_f32_16x16x32_bf16 v[48:51], v[162:165], v[184:187], v[48:51]
	v_mfma_f32_16x16x32_bf16 v[32:35], v[162:165], v[192:195], v[32:35]
	v_mfma_f32_16x16x32_bf16 v[36:39], v[154:157], v[192:195], v[36:39]
	v_mfma_f32_16x16x32_bf16 v[20:23], v[154:157], v[200:203], v[20:23]
	v_mfma_f32_16x16x32_bf16 v[16:19], v[162:165], v[200:203], v[16:19]
	v_mfma_f32_16x16x32_bf16 v[0:3], v[162:165], v[208:211], v[0:3]
	v_mfma_f32_16x16x32_bf16 v[4:7], v[154:157], v[208:211], v[4:7]
	s_barrier
	s_setprio 0
	s_add_i32 s16, 0, 0x18000
	v_add_u32_e32 v128, s16, v174
	s_add_i32 s17, 0, 0x1c000
	ds_read_b128 v[134:137], v128
	ds_read_b128 v[138:141], v128 offset:1024
	ds_read_b128 v[142:145], v180
	ds_read_b128 v[146:149], v180 offset:1024
	v_add_u32_e32 v128, s17, v174
	ds_read_b128 v[150:153], v128
	ds_read_b128 v[154:157], v128 offset:1024
	ds_read_b128 v[158:161], v181
	ds_read_b128 v[162:165], v181 offset:1024
	s_add_u32 s50, s34, 0x100000
	v_mov_b32_e32 v128, v172
	s_mov_b32 m0, s89
	ds_read_b128 v[166:169], v179 offset:32768
	ds_read_b128 v[184:187], v179 offset:33792
	ds_read_b128 v[188:191], v179 offset:34816
	ds_read_b128 v[192:195], v179 offset:35840
	ds_read_b128 v[196:199], v179 offset:36864
	ds_read_b128 v[200:203], v179 offset:37888
	ds_read_b128 v[204:207], v179 offset:38912
	ds_read_b128 v[208:211], v179 offset:39936
	s_addc_u32 s51, s35, 0
	s_nop 0
	global_load_lds_dwordx4 v128, s[50:51]
	v_mov_b32_e32 v128, v173
	s_mov_b32 m0, s90
	s_nop 0
	global_load_lds_dwordx4 v128, s[50:51]
	s_waitcnt vmcnt(8)
	s_waitcnt lgkmcnt(0)
	s_setprio 1
	s_barrier
	v_mfma_f32_16x16x32_bf16 v[124:127], v[134:137], v[166:169], v[124:127]
	v_mfma_f32_16x16x32_bf16 v[120:123], v[142:145], v[166:169], v[120:123]
	v_mfma_f32_16x16x32_bf16 v[104:107], v[142:145], v[188:191], v[104:107]
	v_mfma_f32_16x16x32_bf16 v[108:111], v[134:137], v[188:191], v[108:111]
	v_mfma_f32_16x16x32_bf16 v[92:95], v[134:137], v[196:199], v[92:95]
	v_mfma_f32_16x16x32_bf16 v[88:91], v[142:145], v[196:199], v[88:91]
	v_mfma_f32_16x16x32_bf16 v[72:75], v[142:145], v[204:207], v[72:75]
	v_mfma_f32_16x16x32_bf16 v[76:79], v[134:137], v[204:207], v[76:79]
	s_setprio 0
	s_setprio 1
	v_mfma_f32_16x16x32_bf16 v[124:127], v[138:141], v[184:187], v[124:127]
	v_mfma_f32_16x16x32_bf16 v[120:123], v[146:149], v[184:187], v[120:123]
	v_mfma_f32_16x16x32_bf16 v[104:107], v[146:149], v[192:195], v[104:107]
	v_mfma_f32_16x16x32_bf16 v[108:111], v[138:141], v[192:195], v[108:111]
	v_mfma_f32_16x16x32_bf16 v[92:95], v[138:141], v[200:203], v[92:95]
	v_mfma_f32_16x16x32_bf16 v[88:91], v[146:149], v[200:203], v[88:91]
	v_mfma_f32_16x16x32_bf16 v[72:75], v[146:149], v[208:211], v[72:75]
	v_mfma_f32_16x16x32_bf16 v[76:79], v[138:141], v[208:211], v[76:79]
	s_setprio 0
	s_setprio 1
	v_mfma_f32_16x16x32_bf16 v[116:119], v[150:153], v[166:169], v[116:119]
	v_mfma_f32_16x16x32_bf16 v[112:115], v[158:161], v[166:169], v[112:115]
	v_mfma_f32_16x16x32_bf16 v[96:99], v[158:161], v[188:191], v[96:99]
	v_mfma_f32_16x16x32_bf16 v[100:103], v[150:153], v[188:191], v[100:103]
	v_mfma_f32_16x16x32_bf16 v[84:87], v[150:153], v[196:199], v[84:87]
	v_mfma_f32_16x16x32_bf16 v[80:83], v[158:161], v[196:199], v[80:83]
	v_mfma_f32_16x16x32_bf16 v[64:67], v[158:161], v[204:207], v[64:67]
	v_mfma_f32_16x16x32_bf16 v[68:71], v[150:153], v[204:207], v[68:71]
	s_setprio 0
	s_setprio 1
	v_mfma_f32_16x16x32_bf16 v[116:119], v[154:157], v[184:187], v[116:119]
	v_mfma_f32_16x16x32_bf16 v[112:115], v[162:165], v[184:187], v[112:115]
	v_mfma_f32_16x16x32_bf16 v[96:99], v[162:165], v[192:195], v[96:99]
	v_mfma_f32_16x16x32_bf16 v[100:103], v[154:157], v[192:195], v[100:103]
	v_mfma_f32_16x16x32_bf16 v[84:87], v[154:157], v[200:203], v[84:87]
	v_mfma_f32_16x16x32_bf16 v[80:83], v[162:165], v[200:203], v[80:83]
	v_mfma_f32_16x16x32_bf16 v[64:67], v[162:165], v[208:211], v[64:67]
	v_mfma_f32_16x16x32_bf16 v[68:71], v[154:157], v[208:211], v[68:71]
	s_barrier
; #define PG8_LDA(dst, b, h) do { if constexpr (FP8) { _Pragma("unroll") for (int m = 0; m < 4; ++m) dst##8[m] = PG8_LD8(PG8_SA(b, h), aoff, aoff1, m); } \
;         else { _Pragma("unroll") for (int m = 0; m < 4; ++m) _Pragma("unroll") for (int k = 0; k < 2; ++k) dst[m][k] = *(const LAS bf16x8*)(lds + PG8_SA(b, h) + (k ? aoff1 : aoff) + m * 2048); } } while (0)
; #define PG8_WAIT_V(n) asm volatile("s_waitcnt vmcnt(" #n ")" ::: "memory")
; #define PG8_WAIT_L(n) asm volatile("s_waitcnt lgkmcnt(" #n ")" ::: "memory")
; #define PG8_BAR __builtin_amdgcn_s_barrier()
; #define PG8_SCHED __builtin_amdgcn_sched_barrier(0)
; #define PG8_S4 do { PG8_STAGE(PG8_SB(1, 0), b3, voffB); PG8_STAGE(PG8_SB(1, 1), b3 + hstepB, voffB); PG8_STAGE(PG8_SA(1, 0), a3, voffA); } while (0)
; template <class Epi, class SchedT, bool ALIGN_EPI, bool SP2, bool FP8 = false>
; __device__ __forceinline__ void gemm_phase(LAS unsigned char* lds, const Gemm g, const SchedT& S, const Epi& E, const int wid) {
;     ...
;             PG8_WAIT_V(8); PG8_WAIT_L(0); PG8_BAR; PG8_MMAP(0, 1, 0); PG8_BAR; PG8_SCHED;
;             PG8_LDA(At, 1, 1); PG8_S4;
;             PG8_WAIT_V(8); PG8_WAIT_L(0); PG8_BAR; PG8_MMAP(1, 1, 1); PG8_BAR; PG8_SCHED;
	s_setprio 0
	v_mov_b32_e32 v128, v172
	ds_read_b128 v[166:169], v179 offset:49152
	ds_read_b128 v[184:187], v179 offset:50176
	ds_read_b128 v[188:191], v179 offset:51200
	ds_read_b128 v[192:195], v179 offset:52224
	ds_read_b128 v[196:199], v179 offset:53248
	ds_read_b128 v[200:203], v179 offset:54272
	ds_read_b128 v[204:207], v179 offset:55296
	ds_read_b128 v[208:211], v179 offset:56320
	s_add_i32 s16, s16, s86
	v_lshl_add_u64 v[170:171], s[38:39], 0, v[128:129]
	v_lshl_add_u64 v[170:171], v[170:171], 0, s[8:9]
	s_mov_b32 m0, s16
	v_mov_b32_e32 v128, v173
	global_load_lds_dwordx4 v[170:171], off
	s_add_i32 m0, s16, 0x2000
	s_nop 0
	v_lshl_add_u64 v[170:171], s[38:39], 0, v[128:129]
	s_add_u32 s38, s38, 0x100080
	v_lshl_add_u64 v[170:171], v[170:171], 0, s[8:9]
	s_addc_u32 s39, s39, 0
	v_mov_b32_e32 v128, v172
	s_add_i32 s16, s17, s86
	global_load_lds_dwordx4 v[170:171], off
	s_mov_b32 m0, s16
	s_nop 0
	global_load_lds_dwordx4 v128, s[38:39]
	v_mov_b32_e32 v128, v173
	s_add_i32 m0, s16, 0x2000
	s_nop 0
	global_load_lds_dwordx4 v128, s[38:39]
	v_mov_b32_e32 v128, v172
	s_mov_b32 m0, s92
	v_lshl_add_u64 v[170:171], s[34:35], 0, v[128:129]
	v_lshl_add_u64 v[170:171], v[170:171], 0, s[8:9]
	v_mov_b32_e32 v128, v173
	global_load_lds_dwordx4 v[170:171], off
	s_mov_b32 m0, s93
	v_lshl_add_u64 v[170:171], s[34:35], 0, v[128:129]
	v_lshl_add_u64 v[170:171], v[170:171], 0, s[8:9]
	global_load_lds_dwordx4 v[170:171], off
	s_waitcnt vmcnt(8)
	s_waitcnt lgkmcnt(0)
	s_setprio 1
	s_barrier
	v_mfma_f32_16x16x32_bf16 v[60:63], v[134:137], v[166:169], v[60:63]
	v_mfma_f32_16x16x32_bf16 v[56:59], v[142:145], v[166:169], v[56:59]
	v_mfma_f32_16x16x32_bf16 v[40:43], v[142:145], v[188:191], v[40:43]
	v_mfma_f32_16x16x32_bf16 v[44:47], v[134:137], v[188:191], v[44:47]
	v_mfma_f32_16x16x32_bf16 v[28:31], v[134:137], v[196:199], v[28:31]
	v_mfma_f32_16x16x32_bf16 v[24:27], v[142:145], v[196:199], v[24:27]
	v_mfma_f32_16x16x32_bf16 v[8:11], v[142:145], v[204:207], v[8:11]
	v_mfma_f32_16x16x32_bf16 v[12:15], v[134:137], v[204:207], v[12:15]
	s_setprio 0
	s_setprio 1
	v_mfma_f32_16x16x32_bf16 v[60:63], v[138:141], v[184:187], v[60:63]
	v_mfma_f32_16x16x32_bf16 v[56:59], v[146:149], v[184:187], v[56:59]
	v_mfma_f32_16x16x32_bf16 v[40:43], v[146:149], v[192:195], v[40:43]
	v_mfma_f32_16x16x32_bf16 v[44:47], v[138:141], v[192:195], v[44:47]
	v_mfma_f32_16x16x32_bf16 v[28:31], v[138:141], v[200:203], v[28:31]
	v_mfma_f32_16x16x32_bf16 v[24:27], v[146:149], v[200:203], v[24:27]
	v_mfma_f32_16x16x32_bf16 v[8:11], v[146:149], v[208:211], v[8:11]
	v_mfma_f32_16x16x32_bf16 v[12:15], v[138:141], v[208:211], v[12:15]
	s_setprio 0
	s_setprio 1
	v_mfma_f32_16x16x32_bf16 v[52:55], v[150:153], v[166:169], v[52:55]
	v_mfma_f32_16x16x32_bf16 v[48:51], v[158:161], v[166:169], v[48:51]
	v_mfma_f32_16x16x32_bf16 v[32:35], v[158:161], v[188:191], v[32:35]
	v_mfma_f32_16x16x32_bf16 v[36:39], v[150:153], v[188:191], v[36:39]
	v_mfma_f32_16x16x32_bf16 v[20:23], v[150:153], v[196:199], v[20:23]
	v_mfma_f32_16x16x32_bf16 v[16:19], v[158:161], v[196:199], v[16:19]
	v_mfma_f32_16x16x32_bf16 v[0:3], v[158:161], v[204:207], v[0:3]
	v_mfma_f32_16x16x32_bf16 v[4:7], v[150:153], v[204:207], v[4:7]
	s_setprio 0
	s_setprio 1
	v_mfma_f32_16x16x32_bf16 v[52:55], v[154:157], v[184:187], v[52:55]
	v_mfma_f32_16x16x32_bf16 v[48:51], v[162:165], v[184:187], v[48:51]
	v_mfma_f32_16x16x32_bf16 v[32:35], v[162:165], v[192:195], v[32:35]
	v_mfma_f32_16x16x32_bf16 v[36:39], v[154:157], v[192:195], v[36:39]
	v_mfma_f32_16x16x32_bf16 v[20:23], v[154:157], v[200:203], v[20:23]
	v_mfma_f32_16x16x32_bf16 v[16:19], v[162:165], v[200:203], v[16:19]
	v_mfma_f32_16x16x32_bf16 v[0:3], v[162:165], v[208:211], v[0:3]
	v_mfma_f32_16x16x32_bf16 v[4:7], v[154:157], v[208:211], v[4:7]
	s_barrier
	s_setprio 0
	s_add_u32 s24, s24, 0x100
	s_addc_u32 s25, s25, 0
	s_add_u32 s46, s46, 0x100
	s_addc_u32 s47, s47, 0
	s_cmp_ge_i32 s48, s30
	s_mov_b32 s34, s48
	s_cbranch_scc0 .LBB0_970
	s_and_b64 vcc, exec, s[96:97]
	s_cbranch_vccz .LBB0_973
